# bundle: P5 gn loads hoisted, P8 post_g/post_b resident, attention epilogue gate loads batched, w_in conversion 2 items per trip, rope-table pos prefetch
# speedup vs baseline: 1.1154x; 1.0084x over previous
.LBB0_31:
	s_mov_b32 s6, 0x1948b0fd
	v_mul_hi_i32 v2, v1, s6
	v_lshrrev_b32_e32 v3, 31, v2
	v_ashrrev_i32_e32 v2, 3, v2
	v_add_u32_e32 v4, v2, v3
	s_movk_i32 s6, 0xebc0
	v_mad_u64_u32 v[2:3], s[6:7], v4, s6, v[0:1]
	s_movk_i32 s6, 0x1420
	s_nop 0
	v_cmp_gt_i32_e32 vcc, s6, v2
	s_and_b64 s[32:33], exec, vcc
	v_add_u32_e32 v189, s3, v1
	v_add_u32_e32 v188, s8, v0
	s_mov_b32 s6, 0x1948b0fd
	v_mul_hi_i32 v190, v189, s6
	v_lshrrev_b32_e32 v191, 31, v190
	v_ashrrev_i32_e32 v190, 3, v190
	v_add_u32_e32 v192, v190, v191
	s_movk_i32 s6, 0xebc0
	v_mad_u64_u32 v[190:191], s[6:7], v192, s6, v[188:189]
	s_movk_i32 s6, 0x1420
	s_nop 0
	v_cmp_gt_i32_e32 vcc, s6, v190
	s_and_b64 s[34:35], exec, vcc
	s_movk_i32 s6, 0x2880
	v_cmp_gt_i32_e32 vcc, s6, v189
	s_and_b64 s[34:35], s[34:35], vcc
	s_mov_b64 s[40:41], exec
	s_mov_b64 exec, s[32:33]
	v_readlane_b32 s68, v241, 17
	v_readlane_b32 s78, v241, 27
	v_readlane_b32 s79, v241, 28
	v_lshlrev_b32_e32 v6, 3, v4
	v_ashrrev_i32_e32 v3, 31, v2
	v_mov_b64_e32 v[4:5], s[78:79]
	v_mad_i64_i32 v[4:5], s[10:11], v6, s9, v[4:5]
	v_lshl_add_u64 v[4:5], v[2:3], 2, v[4:5]
	v_add_co_u32_e32 v8, vcc, 0x5000, v4
	v_lshlrev_b64 v[2:3], 11, v[2:3]
	s_nop 0
	v_addc_co_u32_e32 v9, vcc, 0, v5, vcc
	v_add_co_u32_e32 v10, vcc, 0xa000, v4
	v_ashrrev_i32_e32 v7, 31, v6
	s_nop 0
	v_addc_co_u32_e32 v11, vcc, 0, v5, vcc
	v_add_co_u32_e32 v12, vcc, 0xf000, v4
	v_readlane_b32 s69, v241, 18
	s_nop 0
	v_addc_co_u32_e32 v13, vcc, 0, v5, vcc
	v_add_co_u32_e32 v14, vcc, 0x14000, v4
	v_readlane_b32 s70, v241, 19
	s_nop 0
	v_addc_co_u32_e32 v15, vcc, 0, v5, vcc
	v_add_co_u32_e32 v16, vcc, 0x19000, v4
	v_readlane_b32 s71, v241, 20
	s_nop 0
	v_addc_co_u32_e32 v17, vcc, 0, v5, vcc
	v_add_co_u32_e32 v18, vcc, 0x1e000, v4
	v_readlane_b32 s72, v241, 21
	s_nop 0
	v_addc_co_u32_e32 v19, vcc, 0, v5, vcc
	v_add_co_u32_e32 v20, vcc, 0x23000, v4
	v_readlane_b32 s73, v241, 22
	s_nop 0
	v_addc_co_u32_e32 v21, vcc, 0, v5, vcc
	global_load_dword v4, v[4:5], off
	s_nop 0
	global_load_dword v5, v[8:9], off offset:128
	s_nop 0
	global_load_dword v10, v[10:11], off offset:256
	s_nop 0
	global_load_dword v11, v[12:13], off offset:384
	s_nop 0
	global_load_dword v12, v[14:15], off offset:512
	global_load_dword v13, v[16:17], off offset:640
	s_nop 0
	global_load_dword v14, v[18:19], off offset:768
	global_load_dword v15, v[20:21], off offset:896
	v_lshl_add_u64 v[8:9], s[30:31], 0, v[2:3]
	v_lshl_add_u64 v[6:7], v[6:7], 1, v[8:9]
	v_readlane_b32 s74, v241, 23
	v_readlane_b32 s75, v241, 24
	v_readlane_b32 s76, v241, 25
	v_readlane_b32 s77, v241, 26
	v_readlane_b32 s80, v241, 29
	v_readlane_b32 s81, v241, 30
	v_readlane_b32 s82, v241, 31
	v_readlane_b32 s83, v241, 32
	s_mov_b64 exec, s[34:35]
	v_lshlrev_b32_e32 v194, 3, v192
	v_ashrrev_i32_e32 v191, 31, v190
	v_mov_b64_e32 v[192:193], s[78:79]
	v_mad_i64_i32 v[192:193], s[10:11], v194, s9, v[192:193]
	v_lshl_add_u64 v[192:193], v[190:191], 2, v[192:193]
	v_add_co_u32_e32 v196, vcc, 0x5000, v192
	v_lshlrev_b64 v[190:191], 11, v[190:191]
	s_nop 0
	v_addc_co_u32_e32 v197, vcc, 0, v193, vcc
	v_add_co_u32_e32 v198, vcc, 0xa000, v192
	v_ashrrev_i32_e32 v195, 31, v194
	s_nop 0
	v_addc_co_u32_e32 v199, vcc, 0, v193, vcc
	v_add_co_u32_e32 v200, vcc, 0xf000, v192
	s_nop 0
	v_addc_co_u32_e32 v201, vcc, 0, v193, vcc
	v_add_co_u32_e32 v202, vcc, 0x14000, v192
	s_nop 0
	v_addc_co_u32_e32 v203, vcc, 0, v193, vcc
	v_add_co_u32_e32 v204, vcc, 0x19000, v192
	s_nop 0
	v_addc_co_u32_e32 v205, vcc, 0, v193, vcc
	v_add_co_u32_e32 v206, vcc, 0x1e000, v192
	s_nop 0
	v_addc_co_u32_e32 v207, vcc, 0, v193, vcc
	v_add_co_u32_e32 v208, vcc, 0x23000, v192
	s_nop 0
	v_addc_co_u32_e32 v209, vcc, 0, v193, vcc
	global_load_dword v192, v[192:193], off
	s_nop 0
	global_load_dword v193, v[196:197], off offset:128
	s_nop 0
	global_load_dword v198, v[198:199], off offset:256
	s_nop 0
	global_load_dword v199, v[200:201], off offset:384
	s_nop 0
	global_load_dword v200, v[202:203], off offset:512
	global_load_dword v201, v[204:205], off offset:640
	s_nop 0
	global_load_dword v202, v[206:207], off offset:768
	global_load_dword v203, v[208:209], off offset:896
	v_lshl_add_u64 v[196:197], s[30:31], 0, v[190:191]
	v_lshl_add_u64 v[194:195], v[194:195], 1, v[196:197]
	s_mov_b64 exec, s[32:33]
	s_waitcnt vmcnt(8)
	v_cvt_pk_bf16_f32 v2, v4, v5
	v_cvt_pk_bf16_f32 v3, v10, v11
	v_cvt_pk_bf16_f32 v4, v12, v13
	v_cvt_pk_bf16_f32 v5, v14, v15
	s_mov_b64 exec, s[34:35]
	s_waitcnt vmcnt(0)
	v_cvt_pk_bf16_f32 v190, v192, v193
	v_cvt_pk_bf16_f32 v191, v198, v199
	v_cvt_pk_bf16_f32 v192, v200, v201
	v_cvt_pk_bf16_f32 v193, v202, v203
	s_mov_b64 exec, s[32:33]
	global_store_dwordx4 v[6:7], v[2:5], off
	s_mov_b64 exec, s[34:35]
	global_store_dwordx4 v[194:195], v[190:193], off
	s_mov_b64 exec, s[40:41]
	v_add_u32_e32 v1, s3, v189
	v_add_u32_e32 v0, s8, v188
	s_movk_i32 s6, 0x287f
	v_cmp_lt_i32_e32 vcc, s6, v1
	s_or_b64 s[4:5], vcc, s[4:5]
	s_andn2_b64 exec, exec, s[4:5]
	s_cbranch_execnz .LBB0_31

.LBB0_79:
	s_or_b64 exec, exec, s[0:1]
	v_add_u32_e32 v0, v124, v165
	s_mov_b32 s0, 0x80000
	s_lshl_b32 s8, s2, 9
	v_cmp_gt_i32_e32 vcc, s0, v0
	s_and_saveexec_b64 s[12:13], vcc
	s_cbranch_execz .LBB0_86
	v_readlane_b32 s98, v241, 21
	v_readlane_b32 s99, v241, 22
	s_mov_b32 s40, 0
	s_cmp_lg_u32 s8, 0x20000
	s_cbranch_scc1 .Lrope_pf_done
	s_mov_b32 s40, 1
	s_mov_b64 s[42:43], 0x8000
	v_ashrrev_i32_e32 v182, 4, v0
	v_ashrrev_i32_e32 v183, 31, v182
	v_lshl_add_u64 v[182:183], v[182:183], 2, s[98:99]
	global_load_dword v190, v[182:183], off
	v_lshl_add_u64 v[184:185], v[182:183], 0, s[42:43]
	global_load_dword v191, v[184:185], off
	v_lshl_add_u64 v[184:185], v[184:185], 0, s[42:43]
	global_load_dword v192, v[184:185], off
	v_lshl_add_u64 v[184:185], v[184:185], 0, s[42:43]
	global_load_dword v193, v[184:185], off
.Lrope_pf_done:
	v_and_b32_e32 v1, 15, v124
	v_cvt_f64_u32_e32 v[2:3], v1
	v_ldexp_f64 v[4:5], -v[2:3], -4
	v_mov_b32_e32 v2, 0x40c38800
	v_mov_b32_e32 v28, 0x3ff00000
	v_cmp_eq_f64_e32 vcc, 0, v[4:5]
	v_mov_b32_e32 v3, 0
	v_mov_b32_e32 v6, v3
	v_cndmask_b32_e32 v7, v2, v28, vcc
	v_frexp_exp_i32_f64_e32 v2, v[6:7]
	v_frexp_mant_f64_e32 v[6:7], v[6:7]
	s_mov_b32 s5, 0x3fe55555
	s_mov_b32 s4, 0x55555555
	v_cmp_gt_f64_e64 s[0:1], s[4:5], v[6:7]
	s_mov_b32 s7, 0x3fe62e42
	s_mov_b32 s6, 0xfefa39ef
	v_cndmask_b32_e64 v8, 0, 1, s[0:1]
	v_ldexp_f64 v[6:7], v[6:7], v8
	v_add_f64 v[8:9], v[6:7], 1.0
	v_rcp_f64_e32 v[10:11], v[8:9]
	v_add_f64 v[14:15], v[8:9], -1.0
	v_add_f64 v[12:13], v[6:7], -1.0
	v_add_f64 v[6:7], v[6:7], -v[14:15]
	v_fma_f64 v[14:15], -v[8:9], v[10:11], 1.0
	v_fmac_f64_e32 v[10:11], v[14:15], v[10:11]
	v_fma_f64 v[14:15], -v[8:9], v[10:11], 1.0
	v_fmac_f64_e32 v[10:11], v[14:15], v[10:11]
	v_mul_f64 v[14:15], v[12:13], v[10:11]
	v_mul_f64 v[16:17], v[8:9], v[14:15]
	v_fma_f64 v[8:9], v[14:15], v[8:9], -v[16:17]
	v_fmac_f64_e32 v[8:9], v[14:15], v[6:7]
	v_add_f64 v[6:7], v[16:17], v[8:9]
	v_add_f64 v[18:19], v[12:13], -v[6:7]
	v_add_f64 v[16:17], v[6:7], -v[16:17]
	v_add_f64 v[12:13], v[12:13], -v[18:19]
	v_add_f64 v[6:7], v[12:13], -v[6:7]
	v_add_f64 v[8:9], v[16:17], -v[8:9]
	v_add_f64 v[6:7], v[8:9], v[6:7]
	v_add_f64 v[6:7], v[18:19], v[6:7]
	v_mul_f64 v[6:7], v[10:11], v[6:7]
	v_add_f64 v[8:9], v[14:15], v[6:7]
	v_add_f64 v[10:11], v[8:9], -v[14:15]
	v_add_f64 v[6:7], v[6:7], -v[10:11]
	v_mul_f64 v[10:11], v[8:9], v[8:9]
	v_fma_f64 v[12:13], v[8:9], v[8:9], -v[10:11]
	v_add_f64 v[14:15], v[6:7], v[6:7]
	v_fmac_f64_e32 v[12:13], v[8:9], v[14:15]
	v_subbrev_co_u32_e64 v2, s[0:1], 0, v2, s[0:1]
	v_add_f64 v[14:15], v[10:11], v[12:13]
	v_add_f64 v[10:11], v[14:15], -v[10:11]
	s_mov_b32 s0, 0x4222de17
	v_add_f64 v[10:11], v[12:13], -v[10:11]
	v_mov_b32_e32 v12, 0x968915a9
	v_mov_b32_e32 v13, 0x3fba6564
	s_mov_b32 s1, 0x3fbdee67
	v_fmac_f64_e32 v[12:13], s[0:1], v[14:15]
	v_mov_b32_e32 v16, 0x3abe935a
	v_mov_b32_e32 v17, 0x3fbe25e4
	v_fmac_f64_e32 v[16:17], v[14:15], v[12:13]
	v_mov_b32_e32 v12, 0x47e6c9c2
	v_mov_b32_e32 v13, 0x3fc110ef
	v_fmac_f64_e32 v[12:13], v[14:15], v[16:17]
	v_mov_b32_e32 v16, 0xcfa74449
	v_mov_b32_e32 v17, 0x3fc3b13b
	v_fmac_f64_e32 v[16:17], v[14:15], v[12:13]
	v_mov_b32_e32 v12, 0x71bf3c30
	v_mov_b32_e32 v13, 0x3fc745d1
	v_fmac_f64_e32 v[12:13], v[14:15], v[16:17]
	v_mov_b32_e32 v16, 0x1c7792ce
	v_mov_b32_e32 v17, 0x3fcc71c7
	v_fmac_f64_e32 v[16:17], v[14:15], v[12:13]
	v_mov_b32_e32 v12, 0x924920da
	v_mov_b32_e32 v13, 0x3fd24924
	v_fmac_f64_e32 v[12:13], v[14:15], v[16:17]
	v_mov_b32_e32 v16, 0x9999999c
	v_mov_b32_e32 v17, 0x3fd99999
	v_fmac_f64_e32 v[16:17], v[14:15], v[12:13]
	v_cvt_f64_i32_e32 v[12:13], v2
	v_mul_f64 v[18:19], v[12:13], s[6:7]
	v_mul_f64 v[24:25], v[8:9], v[14:15]
	v_fma_f64 v[20:21], v[12:13], s[6:7], -v[18:19]
	s_mov_b32 s69, 0x3c7abc9e
	s_mov_b32 s68, 0x3b39803f
	v_fma_f64 v[26:27], v[14:15], v[8:9], -v[24:25]
	v_fmac_f64_e32 v[20:21], s[68:69], v[12:13]
	v_fmac_f64_e32 v[26:27], v[14:15], v[6:7]
	v_add_f64 v[12:13], v[18:19], v[20:21]
	v_fmac_f64_e32 v[26:27], v[10:11], v[8:9]
	v_add_f64 v[18:19], v[12:13], -v[18:19]
	v_ldexp_f64 v[22:23], v[6:7], 1
	v_add_f64 v[6:7], v[24:25], v[26:27]
	v_add_f64 v[18:19], v[20:21], -v[18:19]
	v_ldexp_f64 v[20:21], v[8:9], 1
	v_add_f64 v[8:9], v[6:7], -v[24:25]
	v_mul_f64 v[24:25], v[14:15], v[16:17]
	v_fma_f64 v[14:15], v[14:15], v[16:17], -v[24:25]
	v_fmac_f64_e32 v[14:15], v[10:11], v[16:17]
	v_add_f64 v[10:11], v[24:25], v[14:15]
	v_add_f64 v[16:17], v[10:11], -v[24:25]
	v_add_f64 v[14:15], v[14:15], -v[16:17]
	v_add_f64 v[16:17], v[10:11], s[4:5]
	s_mov_b32 s5, 0xbfe55555
	s_mov_b32 s0, 0xd5df274d
	v_add_f64 v[24:25], v[16:17], s[4:5]
	s_mov_b32 s1, 0x3c8543b0
	v_add_f64 v[10:11], v[10:11], -v[24:25]
	v_add_f64 v[14:15], v[14:15], s[0:1]
	v_add_f64 v[10:11], v[14:15], v[10:11]
	v_add_f64 v[14:15], v[16:17], v[10:11]
	v_add_f64 v[16:17], v[16:17], -v[14:15]
	v_add_f64 v[10:11], v[10:11], v[16:17]
	v_mul_f64 v[16:17], v[6:7], v[14:15]
	v_fma_f64 v[24:25], v[6:7], v[14:15], -v[16:17]
	v_add_f64 v[8:9], v[26:27], -v[8:9]
	v_fmac_f64_e32 v[24:25], v[6:7], v[10:11]
	v_fmac_f64_e32 v[24:25], v[8:9], v[14:15]
	v_add_f64 v[6:7], v[16:17], v[24:25]
	v_add_f64 v[8:9], v[6:7], -v[16:17]
	v_add_f64 v[10:11], v[20:21], v[6:7]
	v_add_f64 v[8:9], v[24:25], -v[8:9]
	v_add_f64 v[14:15], v[10:11], -v[20:21]
	v_add_f64 v[6:7], v[6:7], -v[14:15]
	v_add_f64 v[8:9], v[22:23], v[8:9]
	v_add_f64 v[6:7], v[8:9], v[6:7]
	v_add_f64 v[8:9], v[10:11], v[6:7]
	v_add_f64 v[10:11], v[8:9], -v[10:11]
	v_add_f64 v[6:7], v[6:7], -v[10:11]
	v_add_f64 v[10:11], v[12:13], v[8:9]
	v_add_f64 v[14:15], v[10:11], -v[12:13]
	v_add_f64 v[16:17], v[10:11], -v[14:15]
	v_add_f64 v[12:13], v[12:13], -v[16:17]
	v_add_f64 v[8:9], v[8:9], -v[14:15]
	v_add_f64 v[8:9], v[8:9], v[12:13]
	v_add_f64 v[12:13], v[18:19], v[6:7]
	v_add_f64 v[14:15], v[12:13], -v[18:19]
	v_add_f64 v[8:9], v[12:13], v[8:9]
	v_add_f64 v[16:17], v[12:13], -v[14:15]
	v_add_f64 v[12:13], v[10:11], v[8:9]
	v_add_f64 v[16:17], v[18:19], -v[16:17]
	v_add_f64 v[6:7], v[6:7], -v[14:15]
	v_add_f64 v[10:11], v[12:13], -v[10:11]
	v_add_f64 v[6:7], v[6:7], v[16:17]
	v_add_f64 v[8:9], v[8:9], -v[10:11]
	v_add_f64 v[6:7], v[6:7], v[8:9]
	v_add_f64 v[8:9], v[12:13], v[6:7]
	v_add_f64 v[10:11], v[8:9], -v[12:13]
	v_add_f64 v[6:7], v[6:7], -v[10:11]
	v_mul_f64 v[10:11], v[4:5], v[8:9]
	v_fma_f64 v[8:9], v[4:5], v[8:9], -v[10:11]
	v_fmac_f64_e32 v[8:9], v[4:5], v[6:7]
	s_movk_i32 s3, 0x204
	v_add_f64 v[6:7], v[10:11], v[8:9]
	v_cmp_class_f64_e64 s[0:1], v[10:11], s3
	v_add_f64 v[12:13], v[6:7], -v[10:11]
	v_add_f64 v[8:9], v[8:9], -v[12:13]
	v_cndmask_b32_e64 v7, v7, v11, s[0:1]
	v_cndmask_b32_e64 v6, v6, v10, s[0:1]
	s_mov_b32 s0, 0
	s_mov_b32 s1, 0x7ff00000
	v_cmp_neq_f64_e64 s[0:1], |v[6:7]|, s[0:1]
	s_mov_b32 s7, 0xbfe62e42
	s_mov_b32 s69, 0xbc7abc9e
	v_cndmask_b32_e64 v9, 0, v9, s[0:1]
	v_cndmask_b32_e64 v8, 0, v8, s[0:1]
	s_mov_b32 s0, 0x652b82fe
	s_mov_b32 s1, 0x3ff71547
	v_mul_f64 v[10:11], v[6:7], s[0:1]
	v_rndne_f64_e32 v[10:11], v[10:11]
	v_fma_f64 v[12:13], s[6:7], v[10:11], v[6:7]
	s_mov_b32 s0, 0x6a5dcb37
	v_fmac_f64_e32 v[12:13], s[68:69], v[10:11]
	v_mov_b32_e32 v14, 0xfca7ab0c
	v_mov_b32_e32 v15, 0x3e928af3
	s_mov_b32 s1, 0x3e5ade15
	v_fmac_f64_e32 v[14:15], s[0:1], v[12:13]
	v_mov_b32_e32 v16, 0x623fde64
	v_mov_b32_e32 v17, 0x3ec71dee
	v_fmac_f64_e32 v[16:17], v[12:13], v[14:15]
	v_mov_b32_e32 v14, 0x7c89e6b0
	v_mov_b32_e32 v15, 0x3efa0199
	v_fmac_f64_e32 v[14:15], v[12:13], v[16:17]
	v_mov_b32_e32 v16, 0x14761f6e
	v_mov_b32_e32 v17, 0x3f2a01a0
	v_fmac_f64_e32 v[16:17], v[12:13], v[14:15]
	v_mov_b32_e32 v14, 0x1852b7b0
	v_mov_b32_e32 v15, 0x3f56c16c
	v_fmac_f64_e32 v[14:15], v[12:13], v[16:17]
	v_mov_b32_e32 v16, 0x11122322
	v_mov_b32_e32 v17, 0x3f811111
	v_fmac_f64_e32 v[16:17], v[12:13], v[14:15]
	v_mov_b32_e32 v14, 0x555502a1
	v_mov_b32_e32 v15, 0x3fa55555
	v_fmac_f64_e32 v[14:15], v[12:13], v[16:17]
	v_mov_b32_e32 v16, 0x55555511
	v_mov_b32_e32 v17, 0x3fc55555
	v_fmac_f64_e32 v[16:17], v[12:13], v[14:15]
	v_mov_b32_e32 v14, 11
	v_mov_b32_e32 v15, 0x3fe00000
	v_fmac_f64_e32 v[14:15], v[12:13], v[16:17]
	v_fma_f64 v[14:15], v[12:13], v[14:15], 1.0
	s_mov_b32 s0, 0
	s_mov_b32 s4, 0
	v_fma_f64 v[12:13], v[12:13], v[14:15], 1.0
	v_cvt_i32_f64_e32 v2, v[10:11]
	s_mov_b32 s1, 0x40900000
	s_mov_b32 s5, 0xc090cc00
	v_ldexp_f64 v[10:11], v[12:13], v2
	v_mov_b32_e32 v2, 0x7ff00000
	v_cmp_nlt_f64_e64 s[0:1], s[0:1], v[6:7]
	v_cmp_ngt_f64_e64 s[4:5], s[4:5], v[6:7]
	s_mov_b32 s68, 0x6dc9c883
	v_cndmask_b32_e64 v11, v2, v11, s[0:1]
	s_and_b64 s[0:1], s[4:5], s[0:1]
	v_cndmask_b32_e64 v7, 0, v11, s[4:5]
	v_cndmask_b32_e64 v6, 0, v10, s[0:1]
	v_mov_b64_e32 v[10:11], v[6:7]
	v_fmac_f64_e32 v[10:11], v[10:11], v[8:9]
	v_cmp_class_f64_e64 s[0:1], v[6:7], s3
	s_mov_b32 s70, 0x54442d18
	s_mov_b64 s[14:15], 0
	v_cndmask_b32_e64 v7, v11, v7, s[0:1]
	v_cndmask_b32_e64 v6, v10, v6, s[0:1]
	v_cmp_neq_f64_e64 s[0:1], v[4:5], |v[4:5]|
	v_and_b32_e32 v7, 0x7fffffff, v7
	s_mov_b32 s69, 0x3fc45f30
	v_cndmask_b32_e64 v2, v2, 0, s[0:1]
	v_cndmask_b32_e32 v2, v2, v28, vcc
	v_cmp_class_f64_e64 vcc, v[4:5], s3
	s_mov_b32 s71, 0xc01921fb
	v_mov_b32_e32 v8, 0x3c0881c4
	v_cndmask_b32_e32 v5, v7, v2, vcc
	v_cndmask_b32_e64 v4, v6, 0, vcc
	v_mov_b32_e32 v9, 0xbab64f3b
	v_not_b32_e32 v10, 63
	v_not_b32_e32 v11, 31
	v_mov_b32_e32 v12, 0x7fc00000
	v_mov_b32_e32 v13, v0
	s_cmp_eq_u32 s40, 1
	s_cbranch_scc1 .Lrope_fast_entry
	s_branch .LBB0_82

.Lrope_fast_entry:
	s_waitcnt vmcnt(0)
	s_branch .Lrope_82

.Lrope_82:
	v_ashrrev_i32_e32 v6, 4, v13
	v_readlane_b32 s72, v241, 17
	v_ashrrev_i32_e32 v7, 31, v6
	v_readlane_b32 s76, v241, 21
	v_readlane_b32 s77, v241, 22
	s_brev_b32 s0, 18
	v_readlane_b32 s73, v241, 18
	v_lshl_add_u64 v[14:15], v[6:7], 2, s[76:77]
	v_mov_b32_e32 v2, v190
	v_mov_b32_e32 v190, v191
	v_mov_b32_e32 v191, v192
	v_mov_b32_e32 v192, v193
	v_readlane_b32 s74, v241, 19
	v_readlane_b32 s75, v241, 20
	v_readlane_b32 s78, v241, 23
	v_readlane_b32 s79, v241, 24
	v_readlane_b32 s80, v241, 25
	v_readlane_b32 s81, v241, 26
	v_readlane_b32 s82, v241, 27
	v_readlane_b32 s83, v241, 28
	v_readlane_b32 s84, v241, 29
	v_readlane_b32 s85, v241, 30
	v_readlane_b32 s86, v241, 31
	v_readlane_b32 s87, v241, 32
	v_cvt_f64_i32_e32 v[14:15], v2
	v_mul_f64 v[14:15], v[4:5], v[14:15]
	v_mul_f64 v[16:17], v[14:15], s[68:69]
	v_rndne_f64_e32 v[16:17], v[16:17]
	v_fmac_f64_e32 v[14:15], s[70:71], v[16:17]
	v_cvt_f32_f64_e32 v7, v[14:15]
	v_and_b32_e32 v14, 0x7fffffff, v7
	v_cmp_nlt_f32_e64 s[0:1], |v7|, s0
	s_and_saveexec_b64 s[4:5], s[0:1]
	s_xor_b64 s[76:77], exec, s[4:5]
	s_cbranch_execz .Lrope_84
	v_lshrrev_b32_e32 v2, 23, v14
	v_add_u32_e32 v2, 0xffffff88, v2
	v_cmp_lt_u32_e32 vcc, 63, v2
	s_mov_b32 s3, 0xfe5163ab
	s_nop 0
	v_cndmask_b32_e32 v15, 0, v10, vcc
	v_add_u32_e32 v2, v15, v2
	v_cmp_lt_u32_e64 s[0:1], 31, v2
	s_nop 1
	v_cndmask_b32_e64 v15, 0, v11, s[0:1]
	v_add_u32_e32 v2, v15, v2
	v_cmp_lt_u32_e64 s[4:5], 31, v2
	s_nop 1
	v_cndmask_b32_e64 v15, 0, v11, s[4:5]
	v_add_u32_e32 v15, v15, v2
	v_and_b32_e32 v2, 0x7fffff, v14
	v_or_b32_e32 v28, 0x800000, v2
	v_mad_u64_u32 v[16:17], s[6:7], v28, s3, 0
	v_mov_b32_e32 v2, v17
	s_mov_b32 s3, 0x3c439041
	v_mad_u64_u32 v[18:19], s[6:7], v28, s3, v[2:3]
	v_mov_b32_e32 v2, v19
	s_mov_b32 s3, 0xdb629599
	v_mad_u64_u32 v[20:21], s[6:7], v28, s3, v[2:3]
	v_mov_b32_e32 v2, v21
	s_mov_b32 s3, 0xf534ddc0
	v_mad_u64_u32 v[22:23], s[6:7], v28, s3, v[2:3]
	v_mov_b32_e32 v2, v23
	s_mov_b32 s3, 0xfc2757d1
	v_mad_u64_u32 v[24:25], s[6:7], v28, s3, v[2:3]
	v_mov_b32_e32 v2, v25
	s_mov_b32 s3, 0x4e441529
	v_mad_u64_u32 v[26:27], s[6:7], v28, s3, v[2:3]
	v_mov_b32_e32 v2, v27
	s_mov_b32 s3, 0xa2f9836e
	v_mad_u64_u32 v[28:29], s[6:7], v28, s3, v[2:3]
	v_cndmask_b32_e32 v17, v26, v22, vcc
	v_cndmask_b32_e32 v2, v28, v24, vcc
	v_cndmask_b32_e32 v21, v29, v26, vcc
	v_cndmask_b32_e64 v19, v2, v17, s[0:1]
	v_cndmask_b32_e64 v2, v21, v2, s[0:1]
	v_cndmask_b32_e32 v21, v24, v20, vcc
	v_cndmask_b32_e64 v17, v17, v21, s[0:1]
	v_cndmask_b32_e64 v2, v2, v19, s[4:5]
	v_cndmask_b32_e64 v19, v19, v17, s[4:5]
	v_sub_u32_e32 v23, 32, v15
	v_alignbit_b32 v24, v2, v19, v23
	v_cmp_eq_u32_e64 s[6:7], 0, v15
	v_cndmask_b32_e32 v16, v20, v16, vcc
	s_nop 0
	v_cndmask_b32_e64 v15, v24, v2, s[6:7]
	v_cndmask_b32_e32 v2, v22, v18, vcc
	v_cndmask_b32_e64 v18, v21, v2, s[0:1]
	v_cndmask_b32_e64 v17, v17, v18, s[4:5]
	v_alignbit_b32 v21, v19, v17, v23
	v_cndmask_b32_e64 v19, v21, v19, s[6:7]
	v_bfe_u32 v24, v15, 29, 1
	v_cndmask_b32_e64 v2, v2, v16, s[0:1]
	v_alignbit_b32 v21, v15, v19, 30
	v_sub_u32_e32 v25, 0, v24
	v_cndmask_b32_e64 v2, v18, v2, s[4:5]
	v_xor_b32_e32 v21, v21, v25
	v_alignbit_b32 v16, v17, v2, v23
	v_cndmask_b32_e64 v16, v16, v17, s[6:7]
	v_ffbh_u32_e32 v18, v21
	v_alignbit_b32 v17, v19, v16, 30
	v_min_u32_e32 v18, 32, v18
	v_alignbit_b32 v2, v16, v2, 30
	v_xor_b32_e32 v17, v17, v25
	v_sub_u32_e32 v19, 31, v18
	v_xor_b32_e32 v2, v2, v25
	v_alignbit_b32 v20, v21, v17, v19
	v_alignbit_b32 v2, v17, v2, v19
	v_alignbit_b32 v16, v20, v2, 9
	v_ffbh_u32_e32 v17, v16
	v_min_u32_e32 v17, 32, v17
	v_lshrrev_b32_e32 v22, 29, v15
	v_not_b32_e32 v19, v17
	v_alignbit_b32 v2, v16, v2, v19
	v_lshlrev_b32_e32 v16, 31, v22
	v_or_b32_e32 v19, 0x33000000, v16
	v_add_lshl_u32 v17, v17, v18, 23
	v_lshrrev_b32_e32 v2, 9, v2
	v_sub_u32_e32 v17, v19, v17
	v_or_b32_e32 v16, 0.5, v16
	v_lshlrev_b32_e32 v18, 23, v18
	v_or_b32_e32 v2, v17, v2
	v_lshrrev_b32_e32 v17, 9, v20
	v_sub_u32_e32 v16, v16, v18
	v_or_b32_e32 v16, v17, v16
	v_mul_f32_e32 v17, 0x3fc90fda, v16
	s_mov_b32 s0, 0x3fc90fda
	v_fma_f32 v18, v16, s0, -v17
	v_fmac_f32_e32 v18, 0x33a22168, v16
	v_fmac_f32_e32 v18, 0x3fc90fda, v2
	v_lshrrev_b32_e32 v15, 30, v15
	v_add_f32_e32 v2, v17, v18
	v_add_u32_e32 v15, v24, v15

.LBB0_1062:
	s_or_b64 exec, exec, s[22:23]
	s_waitcnt lgkmcnt(0)
	s_barrier
	s_and_saveexec_b64 s[0:1], vcc
	s_cbranch_execz .LBB0_1035
	s_lshl_b32 s4, s41, 9
	s_and_b32 s4, s4, 0x7000
	s_add_i32 s4, s4, s55
	v_readlane_b32 s68, v240, 1
	v_lshl_add_u64 v[64:65], v[164:165], 0, s[4:5]
	v_readlane_b32 s74, v240, 7
	v_readlane_b32 s75, v240, 8
	v_or_b32_e32 v64, v64, v159
	s_lshl_b32 s4, s41, 7
	v_mov_b64_e32 v[66:67], s[74:75]
	v_mad_u64_u32 v[68:69], s[22:23], v64, s39, v[66:67]
	v_mad_i32_i24 v69, v65, s39, v69
	s_and_b32 s4, s4, 0x380
	v_lshl_add_u64 v[68:69], v[68:69], 0, s[4:5]
	v_mov_b32_e32 v159, v157
	v_lshl_add_u64 v[68:69], v[68:69], 0, v[158:159]
	global_load_dwordx2 v[176:177], v[68:69], off
	global_load_dwordx2 v[178:179], v[68:69], off offset:16
	global_load_dwordx2 v[180:181], v[68:69], off offset:32
	global_load_dwordx2 v[182:183], v[68:69], off offset:48
	global_load_dwordx2 v[184:185], v[68:69], off offset:64
	global_load_dwordx2 v[186:187], v[68:69], off offset:80
	global_load_dwordx2 v[188:189], v[68:69], off offset:96
	global_load_dwordx2 v[190:191], v[68:69], off offset:112
	s_mov_b32 s98, 0x30000
	s_mov_b32 s99, 0
	v_lshl_add_u64 v[208:209], v[68:69], 0, s[98:99]
	global_load_dwordx2 v[192:193], v[208:209], off
	global_load_dwordx2 v[194:195], v[208:209], off offset:16
	global_load_dwordx2 v[196:197], v[208:209], off offset:32
	global_load_dwordx2 v[198:199], v[208:209], off offset:48
	global_load_dwordx2 v[200:201], v[208:209], off offset:64
	global_load_dwordx2 v[202:203], v[208:209], off offset:80
	global_load_dwordx2 v[204:205], v[208:209], off offset:96
	global_load_dwordx2 v[206:207], v[208:209], off offset:112
	ds_read2st64_b32 v[78:79], v83 offset1:1
	v_max_f32_e32 v86, v161, v161
	ds_read2st64_b32 v[72:73], v82 offset1:1
	ds_read2st64_b32 v[74:75], v82 offset0:2 offset1:3
	ds_read2st64_b32 v[76:77], v82 offset0:4 offset1:5
	ds_read2st64_b32 v[80:81], v82 offset0:6 offset1:7
	ds_read2st64_b32 v[84:85], v83 offset0:2 offset1:3
	v_readlane_b32 s76, v240, 9
	v_readlane_b32 s77, v240, 10
	s_waitcnt lgkmcnt(5)
	v_max_f32_e32 v83, v78, v78
	v_mov_b32_e32 v163, v79
	v_max_f32_e32 v79, v86, v83
	v_sub_f32_e32 v83, v161, v79
	v_sub_f32_e32 v79, v78, v79
	v_exp_f32_e32 v78, v83
	v_exp_f32_e32 v79, v79
	v_readlane_b32 s78, v240, 11
	v_readlane_b32 s79, v240, 12
	v_readlane_b32 s80, v240, 13
	v_pk_mul_f32 v[88:89], v[162:163], v[78:79]
	v_readlane_b32 s81, v240, 14
	v_add_f32_e32 v83, v88, v89
	v_div_scale_f32 v88, s[22:23], v83, v83, 1.0
	v_rcp_f32_e32 v89, v88
	v_div_scale_f32 v90, vcc, 1.0, v83, 1.0
	v_readlane_b32 s82, v240, 15
	v_fma_f32 v91, -v88, v89, 1.0
	v_fmac_f32_e32 v89, v91, v89
	v_mul_f32_e32 v91, v90, v89
	v_fma_f32 v92, -v88, v91, v90
	v_fmac_f32_e32 v91, v92, v89
	v_fma_f32 v88, -v88, v91, v90
	v_div_fmas_f32 v88, v88, v89, v91
	v_div_fixup_f32 v83, v88, v83, 1.0
	v_readlane_b32 s83, v240, 16
	s_mov_b64 s[44:45], s[76:77]
	v_mul_f32_e32 v88, v79, v83
	s_mov_b64 s[50:51], s[82:83]
	v_lshlrev_b64 v[86:87], 11, v[64:65]
	v_mul_f32_e32 v78, v78, v83
	s_waitcnt lgkmcnt(4)
	v_pk_mul_f32 v[72:73], v[72:73], v[88:89] op_sel_hi:[1,0]
	s_waitcnt lgkmcnt(3)
	v_pk_mul_f32 v[74:75], v[74:75], v[88:89] op_sel_hi:[1,0]
	v_lshl_add_u64 v[86:87], s[50:51], 0, v[86:87]
	v_pk_fma_f32 v[48:49], v[48:49], v[78:79], v[72:73] op_sel_hi:[1,0,1]
	v_pk_fma_f32 v[50:51], v[50:51], v[78:79], v[74:75] op_sel_hi:[1,0,1]
	v_lshl_add_u64 v[86:87], v[86:87], 0, s[4:5]
	v_lshl_add_u64 v[86:87], v[86:87], 0, v[158:159]
	v_or_b32_e32 v64, 32, v64
	s_waitcnt lgkmcnt(0)
	v_mov_b32_e32 v161, v85
	v_readlane_b32 s69, v240, 2
	v_readlane_b32 s70, v240, 3
	v_readlane_b32 s71, v240, 4
	v_readlane_b32 s72, v240, 5
	v_readlane_b32 s73, v240, 6
	s_mov_b64 s[46:47], s[78:79]
	s_mov_b64 s[48:49], s[80:81]
	s_waitcnt vmcnt(15)
	v_mov_b32_e32 v70, v176
	v_mov_b32_e32 v71, v177
	v_lshlrev_b32_e32 v72, 16, v70
	v_and_b32_e32 v73, 0xffff0000, v70
	v_lshlrev_b32_e32 v70, 16, v71
	v_and_b32_e32 v71, 0xffff0000, v71
	v_pk_mul_f32 v[48:49], v[48:49], v[72:73]
	v_pk_mul_f32 v[50:51], v[50:51], v[70:71]
	v_cvt_pk_bf16_f32 v48, v48, v49
	v_cvt_pk_bf16_f32 v49, v50, v51
	global_store_dwordx2 v[86:87], v[48:49], off
	v_pk_mul_f32 v[50:51], v[88:89], v[76:77] op_sel_hi:[0,1]
	v_pk_mul_f32 v[70:71], v[88:89], v[80:81] op_sel_hi:[0,1]
	v_pk_fma_f32 v[50:51], v[52:53], v[78:79], v[50:51] op_sel_hi:[1,0,1]
	v_pk_fma_f32 v[52:53], v[54:55], v[78:79], v[70:71] op_sel_hi:[1,0,1]
	s_waitcnt vmcnt(15)
	v_mov_b32_e32 v48, v178
	v_mov_b32_e32 v49, v179
	v_lshlrev_b32_e32 v54, 16, v48
	v_and_b32_e32 v55, 0xffff0000, v48
	v_lshlrev_b32_e32 v48, 16, v49
	v_and_b32_e32 v49, 0xffff0000, v49
	v_pk_mul_f32 v[50:51], v[50:51], v[54:55]
	v_pk_mul_f32 v[48:49], v[52:53], v[48:49]
	v_cvt_pk_bf16_f32 v50, v50, v51
	v_cvt_pk_bf16_f32 v51, v48, v49
	global_store_dwordx2 v[86:87], v[50:51], off offset:16
	ds_read2st64_b32 v[50:51], v82 offset0:8 offset1:9
	ds_read2st64_b32 v[52:53], v82 offset0:10 offset1:11
	ds_read2st64_b32 v[54:55], v82 offset0:12 offset1:13
	ds_read2st64_b32 v[70:71], v82 offset0:14 offset1:15
	s_waitcnt lgkmcnt(3)
	v_pk_mul_f32 v[50:51], v[88:89], v[50:51] op_sel_hi:[0,1]
	s_waitcnt lgkmcnt(2)
	v_pk_mul_f32 v[52:53], v[88:89], v[52:53] op_sel_hi:[0,1]
	v_pk_fma_f32 v[50:51], v[56:57], v[78:79], v[50:51] op_sel_hi:[1,0,1]
	v_pk_fma_f32 v[52:53], v[58:59], v[78:79], v[52:53] op_sel_hi:[1,0,1]
	s_waitcnt vmcnt(15)
	v_mov_b32_e32 v48, v180
	v_mov_b32_e32 v49, v181
	v_lshlrev_b32_e32 v56, 16, v48
	v_and_b32_e32 v57, 0xffff0000, v48
	v_lshlrev_b32_e32 v48, 16, v49
	v_and_b32_e32 v49, 0xffff0000, v49
	v_pk_mul_f32 v[50:51], v[50:51], v[56:57]
	v_pk_mul_f32 v[48:49], v[52:53], v[48:49]
	v_cvt_pk_bf16_f32 v50, v50, v51
	v_cvt_pk_bf16_f32 v51, v48, v49
	global_store_dwordx2 v[86:87], v[50:51], off offset:32
	s_waitcnt lgkmcnt(1)
	v_pk_mul_f32 v[50:51], v[88:89], v[54:55] op_sel_hi:[0,1]
	s_waitcnt lgkmcnt(0)
	v_pk_mul_f32 v[52:53], v[88:89], v[70:71] op_sel_hi:[0,1]
	v_pk_fma_f32 v[50:51], v[60:61], v[78:79], v[50:51] op_sel_hi:[1,0,1]
	v_pk_fma_f32 v[52:53], v[62:63], v[78:79], v[52:53] op_sel_hi:[1,0,1]
	s_waitcnt vmcnt(15)
	v_mov_b32_e32 v48, v182
	v_mov_b32_e32 v49, v183
	v_lshlrev_b32_e32 v54, 16, v48
	v_and_b32_e32 v55, 0xffff0000, v48
	v_lshlrev_b32_e32 v48, 16, v49
	v_and_b32_e32 v49, 0xffff0000, v49
	v_pk_mul_f32 v[50:51], v[50:51], v[54:55]
	v_pk_mul_f32 v[48:49], v[52:53], v[48:49]
	v_cvt_pk_bf16_f32 v50, v50, v51
	v_cvt_pk_bf16_f32 v51, v48, v49
	global_store_dwordx2 v[86:87], v[50:51], off offset:48
	ds_read2st64_b32 v[50:51], v82 offset0:16 offset1:17
	ds_read2st64_b32 v[52:53], v82 offset0:18 offset1:19
	ds_read2st64_b32 v[54:55], v82 offset0:20 offset1:21
	ds_read2st64_b32 v[56:57], v82 offset0:22 offset1:23
	s_waitcnt lgkmcnt(3)
	v_pk_mul_f32 v[50:51], v[88:89], v[50:51] op_sel_hi:[0,1]
	s_waitcnt lgkmcnt(2)
	v_pk_mul_f32 v[52:53], v[88:89], v[52:53] op_sel_hi:[0,1]
	v_pk_fma_f32 v[32:33], v[32:33], v[78:79], v[50:51] op_sel_hi:[1,0,1]
	v_pk_fma_f32 v[34:35], v[34:35], v[78:79], v[52:53] op_sel_hi:[1,0,1]
	s_waitcnt vmcnt(15)
	v_mov_b32_e32 v48, v184
	v_mov_b32_e32 v49, v185
	v_lshlrev_b32_e32 v50, 16, v48
	v_and_b32_e32 v51, 0xffff0000, v48
	v_lshlrev_b32_e32 v48, 16, v49
	v_and_b32_e32 v49, 0xffff0000, v49
	v_pk_mul_f32 v[32:33], v[32:33], v[50:51]
	v_pk_mul_f32 v[34:35], v[34:35], v[48:49]
	v_cvt_pk_bf16_f32 v32, v32, v33
	v_cvt_pk_bf16_f32 v33, v34, v35
	global_store_dwordx2 v[86:87], v[32:33], off offset:64
	s_waitcnt lgkmcnt(1)
	v_pk_mul_f32 v[34:35], v[88:89], v[54:55] op_sel_hi:[0,1]
	s_waitcnt lgkmcnt(0)
	v_pk_mul_f32 v[48:49], v[88:89], v[56:57] op_sel_hi:[0,1]
	v_pk_fma_f32 v[34:35], v[36:37], v[78:79], v[34:35] op_sel_hi:[1,0,1]
	v_pk_fma_f32 v[36:37], v[38:39], v[78:79], v[48:49] op_sel_hi:[1,0,1]
	s_waitcnt vmcnt(15)
	v_mov_b32_e32 v32, v186
	v_mov_b32_e32 v33, v187
	v_lshlrev_b32_e32 v38, 16, v32
	v_and_b32_e32 v39, 0xffff0000, v32
	v_lshlrev_b32_e32 v32, 16, v33
	v_and_b32_e32 v33, 0xffff0000, v33
	v_pk_mul_f32 v[34:35], v[34:35], v[38:39]
	v_pk_mul_f32 v[32:33], v[36:37], v[32:33]
	v_cvt_pk_bf16_f32 v34, v34, v35
	v_cvt_pk_bf16_f32 v35, v32, v33
	global_store_dwordx2 v[86:87], v[34:35], off offset:80
	ds_read2st64_b32 v[34:35], v82 offset0:24 offset1:25
	ds_read2st64_b32 v[36:37], v82 offset0:26 offset1:27
	ds_read2st64_b32 v[38:39], v82 offset0:28 offset1:29
	ds_read2st64_b32 v[48:49], v82 offset0:30 offset1:31
	s_waitcnt lgkmcnt(3)
	v_pk_mul_f32 v[34:35], v[88:89], v[34:35] op_sel_hi:[0,1]
	s_waitcnt lgkmcnt(2)
	v_pk_mul_f32 v[36:37], v[88:89], v[36:37] op_sel_hi:[0,1]
	v_pk_fma_f32 v[34:35], v[40:41], v[78:79], v[34:35] op_sel_hi:[1,0,1]
	v_pk_fma_f32 v[36:37], v[42:43], v[78:79], v[36:37] op_sel_hi:[1,0,1]
	s_waitcnt vmcnt(15)
	v_mov_b32_e32 v32, v188
	v_mov_b32_e32 v33, v189
	v_lshlrev_b32_e32 v40, 16, v32
	v_and_b32_e32 v41, 0xffff0000, v32
	v_lshlrev_b32_e32 v32, 16, v33
	v_and_b32_e32 v33, 0xffff0000, v33
	v_pk_mul_f32 v[34:35], v[34:35], v[40:41]
	v_pk_mul_f32 v[32:33], v[36:37], v[32:33]
	v_cvt_pk_bf16_f32 v34, v34, v35
	v_cvt_pk_bf16_f32 v35, v32, v33
	global_store_dwordx2 v[86:87], v[34:35], off offset:96
	s_waitcnt lgkmcnt(1)
	v_pk_mul_f32 v[36:37], v[88:89], v[38:39] op_sel_hi:[0,1]
	s_waitcnt lgkmcnt(0)
	v_pk_mul_f32 v[38:39], v[88:89], v[48:49] op_sel_hi:[0,1]
	v_mad_u64_u32 v[32:33], s[22:23], v64, s39, v[66:67]
	v_pk_fma_f32 v[36:37], v[44:45], v[78:79], v[36:37] op_sel_hi:[1,0,1]
	v_pk_fma_f32 v[38:39], v[46:47], v[78:79], v[38:39] op_sel_hi:[1,0,1]
	v_mad_i32_i24 v33, v65, s39, v33
	v_lshl_add_u64 v[32:33], v[32:33], 0, s[4:5]
	v_lshl_add_u64 v[32:33], v[32:33], 0, v[158:159]
	s_waitcnt vmcnt(15)
	v_mov_b32_e32 v34, v190
	v_mov_b32_e32 v35, v191
	v_lshlrev_b32_e32 v40, 16, v34
	v_and_b32_e32 v41, 0xffff0000, v34
	v_lshlrev_b32_e32 v34, 16, v35
	v_and_b32_e32 v35, 0xffff0000, v35
	v_pk_mul_f32 v[36:37], v[36:37], v[40:41]
	v_pk_mul_f32 v[34:35], v[38:39], v[34:35]
	v_cvt_pk_bf16_f32 v36, v36, v37
	v_cvt_pk_bf16_f32 v37, v34, v35
	global_store_dwordx2 v[86:87], v[36:37], off offset:112
	v_max_f32_e32 v34, v167, v167
	v_max_f32_e32 v35, v84, v84
	v_max_f32_e32 v34, v34, v35
	v_sub_f32_e32 v35, v167, v34
	v_sub_f32_e32 v34, v84, v34
	v_exp_f32_e32 v36, v35
	v_exp_f32_e32 v37, v34
	ds_read2st64_b32 v[42:43], v82 offset0:32 offset1:33
	ds_read2st64_b32 v[44:45], v82 offset0:34 offset1:35
	ds_read2st64_b32 v[46:47], v82 offset0:36 offset1:37
	ds_read2st64_b32 v[48:49], v82 offset0:38 offset1:39
	v_lshlrev_b64 v[34:35], 11, v[64:65]
	v_lshl_add_u64 v[34:35], s[50:51], 0, v[34:35]
	v_pk_mul_f32 v[38:39], v[160:161], v[36:37]
	v_lshl_add_u64 v[34:35], v[34:35], 0, s[4:5]
	v_add_f32_e32 v38, v38, v39
	v_div_scale_f32 v39, s[22:23], v38, v38, 1.0
	v_rcp_f32_e32 v50, v39
	v_div_scale_f32 v51, vcc, 1.0, v38, 1.0
	v_lshl_add_u64 v[34:35], v[34:35], 0, v[158:159]
	v_fma_f32 v52, -v39, v50, 1.0
	v_fmac_f32_e32 v50, v52, v50
	v_mul_f32_e32 v52, v51, v50
	v_fma_f32 v53, -v39, v52, v51
	v_fmac_f32_e32 v52, v53, v50
	v_fma_f32 v39, -v39, v52, v51
	v_div_fmas_f32 v39, v39, v50, v52
	v_div_fixup_f32 v38, v39, v38, 1.0
	v_mul_f32_e32 v36, v36, v38
	v_mul_f32_e32 v38, v37, v38
	s_waitcnt lgkmcnt(3)
	v_pk_mul_f32 v[42:43], v[42:43], v[38:39] op_sel_hi:[1,0]
	s_waitcnt lgkmcnt(2)
	v_pk_mul_f32 v[44:45], v[44:45], v[38:39] op_sel_hi:[1,0]
	v_pk_fma_f32 v[16:17], v[16:17], v[36:37], v[42:43] op_sel_hi:[1,0,1]
	v_pk_fma_f32 v[18:19], v[18:19], v[36:37], v[44:45] op_sel_hi:[1,0,1]
	s_waitcnt vmcnt(15)
	v_mov_b32_e32 v40, v192
	v_mov_b32_e32 v41, v193
	v_lshlrev_b32_e32 v42, 16, v40
	v_and_b32_e32 v43, 0xffff0000, v40
	v_lshlrev_b32_e32 v40, 16, v41
	v_and_b32_e32 v41, 0xffff0000, v41
	v_pk_mul_f32 v[16:17], v[16:17], v[42:43]
	v_pk_mul_f32 v[18:19], v[18:19], v[40:41]
	v_cvt_pk_bf16_f32 v16, v16, v17
	v_cvt_pk_bf16_f32 v17, v18, v19
	global_store_dwordx2 v[34:35], v[16:17], off
	s_waitcnt lgkmcnt(1)
	v_pk_mul_f32 v[18:19], v[38:39], v[46:47] op_sel_hi:[0,1]
	s_waitcnt lgkmcnt(0)
	v_pk_mul_f32 v[40:41], v[38:39], v[48:49] op_sel_hi:[0,1]
	v_pk_fma_f32 v[18:19], v[20:21], v[36:37], v[18:19] op_sel_hi:[1,0,1]
	v_pk_fma_f32 v[20:21], v[22:23], v[36:37], v[40:41] op_sel_hi:[1,0,1]
	s_waitcnt vmcnt(15)
	v_mov_b32_e32 v16, v194
	v_mov_b32_e32 v17, v195
	v_lshlrev_b32_e32 v22, 16, v16
	v_and_b32_e32 v23, 0xffff0000, v16
	v_lshlrev_b32_e32 v16, 16, v17
	v_and_b32_e32 v17, 0xffff0000, v17
	v_pk_mul_f32 v[18:19], v[18:19], v[22:23]
	v_pk_mul_f32 v[16:17], v[20:21], v[16:17]
	v_cvt_pk_bf16_f32 v18, v18, v19
	v_cvt_pk_bf16_f32 v19, v16, v17
	global_store_dwordx2 v[34:35], v[18:19], off offset:16
	ds_read2st64_b32 v[18:19], v82 offset0:40 offset1:41
	ds_read2st64_b32 v[20:21], v82 offset0:42 offset1:43
	ds_read2st64_b32 v[22:23], v82 offset0:44 offset1:45
	ds_read2st64_b32 v[40:41], v82 offset0:46 offset1:47
	s_waitcnt lgkmcnt(3)
	v_pk_mul_f32 v[18:19], v[38:39], v[18:19] op_sel_hi:[0,1]
	s_waitcnt lgkmcnt(2)
	v_pk_mul_f32 v[20:21], v[38:39], v[20:21] op_sel_hi:[0,1]
	v_pk_fma_f32 v[18:19], v[24:25], v[36:37], v[18:19] op_sel_hi:[1,0,1]
	v_pk_fma_f32 v[20:21], v[26:27], v[36:37], v[20:21] op_sel_hi:[1,0,1]
	s_waitcnt vmcnt(15)
	v_mov_b32_e32 v16, v196
	v_mov_b32_e32 v17, v197
	v_lshlrev_b32_e32 v24, 16, v16
	v_and_b32_e32 v25, 0xffff0000, v16
	v_lshlrev_b32_e32 v16, 16, v17
	v_and_b32_e32 v17, 0xffff0000, v17
	v_pk_mul_f32 v[18:19], v[18:19], v[24:25]
	v_pk_mul_f32 v[16:17], v[20:21], v[16:17]
	v_cvt_pk_bf16_f32 v18, v18, v19
	v_cvt_pk_bf16_f32 v19, v16, v17
	global_store_dwordx2 v[34:35], v[18:19], off offset:32
	s_waitcnt lgkmcnt(1)
	v_pk_mul_f32 v[18:19], v[38:39], v[22:23] op_sel_hi:[0,1]
	s_waitcnt lgkmcnt(0)
	v_pk_mul_f32 v[20:21], v[38:39], v[40:41] op_sel_hi:[0,1]
	v_pk_fma_f32 v[18:19], v[28:29], v[36:37], v[18:19] op_sel_hi:[1,0,1]
	v_pk_fma_f32 v[20:21], v[30:31], v[36:37], v[20:21] op_sel_hi:[1,0,1]
	s_waitcnt vmcnt(15)
	v_mov_b32_e32 v16, v198
	v_mov_b32_e32 v17, v199
	v_lshlrev_b32_e32 v22, 16, v16
	v_and_b32_e32 v23, 0xffff0000, v16
	v_lshlrev_b32_e32 v16, 16, v17
	v_and_b32_e32 v17, 0xffff0000, v17
	v_pk_mul_f32 v[18:19], v[18:19], v[22:23]
	v_pk_mul_f32 v[16:17], v[20:21], v[16:17]
	v_cvt_pk_bf16_f32 v18, v18, v19
	v_cvt_pk_bf16_f32 v19, v16, v17
	global_store_dwordx2 v[34:35], v[18:19], off offset:48
	ds_read2st64_b32 v[18:19], v82 offset0:48 offset1:49
	ds_read2st64_b32 v[20:21], v82 offset0:50 offset1:51
	ds_read2st64_b32 v[22:23], v82 offset0:52 offset1:53
	ds_read2st64_b32 v[24:25], v82 offset0:54 offset1:55
	s_waitcnt lgkmcnt(3)
	v_pk_mul_f32 v[18:19], v[38:39], v[18:19] op_sel_hi:[0,1]
	s_waitcnt lgkmcnt(2)
	v_pk_mul_f32 v[20:21], v[38:39], v[20:21] op_sel_hi:[0,1]
	v_pk_fma_f32 v[0:1], v[0:1], v[36:37], v[18:19] op_sel_hi:[1,0,1]
	v_pk_fma_f32 v[2:3], v[2:3], v[36:37], v[20:21] op_sel_hi:[1,0,1]
	s_waitcnt vmcnt(15)
	v_mov_b32_e32 v16, v200
	v_mov_b32_e32 v17, v201
	v_lshlrev_b32_e32 v18, 16, v16
	v_and_b32_e32 v19, 0xffff0000, v16
	v_lshlrev_b32_e32 v16, 16, v17
	v_and_b32_e32 v17, 0xffff0000, v17
	v_pk_mul_f32 v[0:1], v[0:1], v[18:19]
	v_pk_mul_f32 v[2:3], v[2:3], v[16:17]
	v_cvt_pk_bf16_f32 v0, v0, v1
	v_cvt_pk_bf16_f32 v1, v2, v3
	global_store_dwordx2 v[34:35], v[0:1], off offset:64
	s_waitcnt lgkmcnt(1)
	v_pk_mul_f32 v[2:3], v[38:39], v[22:23] op_sel_hi:[0,1]
	s_waitcnt lgkmcnt(0)
	v_pk_mul_f32 v[16:17], v[38:39], v[24:25] op_sel_hi:[0,1]
	v_pk_fma_f32 v[2:3], v[4:5], v[36:37], v[2:3] op_sel_hi:[1,0,1]
	v_pk_fma_f32 v[4:5], v[6:7], v[36:37], v[16:17] op_sel_hi:[1,0,1]
	s_waitcnt vmcnt(15)
	v_mov_b32_e32 v0, v202
	v_mov_b32_e32 v1, v203
	v_lshlrev_b32_e32 v6, 16, v0
	v_and_b32_e32 v7, 0xffff0000, v0
	v_lshlrev_b32_e32 v0, 16, v1
	v_and_b32_e32 v1, 0xffff0000, v1
	v_pk_mul_f32 v[2:3], v[2:3], v[6:7]
	v_pk_mul_f32 v[0:1], v[4:5], v[0:1]
	v_cvt_pk_bf16_f32 v2, v2, v3
	v_cvt_pk_bf16_f32 v3, v0, v1
	global_store_dwordx2 v[34:35], v[2:3], off offset:80
	ds_read2st64_b32 v[2:3], v82 offset0:56 offset1:57
	ds_read2st64_b32 v[4:5], v82 offset0:58 offset1:59
	ds_read2st64_b32 v[6:7], v82 offset0:60 offset1:61
	ds_read2st64_b32 v[16:17], v82 offset0:62 offset1:63
	s_waitcnt lgkmcnt(3)
	v_pk_mul_f32 v[2:3], v[38:39], v[2:3] op_sel_hi:[0,1]
	s_waitcnt lgkmcnt(2)
	v_pk_mul_f32 v[4:5], v[38:39], v[4:5] op_sel_hi:[0,1]
	v_pk_fma_f32 v[2:3], v[8:9], v[36:37], v[2:3] op_sel_hi:[1,0,1]
	v_pk_fma_f32 v[4:5], v[10:11], v[36:37], v[4:5] op_sel_hi:[1,0,1]
	s_waitcnt vmcnt(15)
	v_mov_b32_e32 v0, v204
	v_mov_b32_e32 v1, v205
	v_lshlrev_b32_e32 v8, 16, v0
	v_and_b32_e32 v9, 0xffff0000, v0
	v_lshlrev_b32_e32 v0, 16, v1
	v_and_b32_e32 v1, 0xffff0000, v1
	v_pk_mul_f32 v[2:3], v[2:3], v[8:9]
	v_pk_mul_f32 v[0:1], v[4:5], v[0:1]
	v_cvt_pk_bf16_f32 v2, v2, v3
	v_cvt_pk_bf16_f32 v3, v0, v1
	global_store_dwordx2 v[34:35], v[2:3], off offset:96
	s_waitcnt lgkmcnt(1)
	v_pk_mul_f32 v[2:3], v[38:39], v[6:7] op_sel_hi:[0,1]
	s_waitcnt lgkmcnt(0)
	v_pk_mul_f32 v[4:5], v[38:39], v[16:17] op_sel_hi:[0,1]
	v_pk_fma_f32 v[2:3], v[12:13], v[36:37], v[2:3] op_sel_hi:[1,0,1]
	v_pk_fma_f32 v[4:5], v[14:15], v[36:37], v[4:5] op_sel_hi:[1,0,1]
	s_waitcnt vmcnt(15)
	v_mov_b32_e32 v0, v206
	v_mov_b32_e32 v1, v207
	v_lshlrev_b32_e32 v6, 16, v0
	v_and_b32_e32 v7, 0xffff0000, v0
	v_lshlrev_b32_e32 v0, 16, v1
	v_and_b32_e32 v1, 0xffff0000, v1
	v_pk_mul_f32 v[2:3], v[2:3], v[6:7]
	v_pk_mul_f32 v[0:1], v[4:5], v[0:1]
	v_cvt_pk_bf16_f32 v2, v2, v3
	v_cvt_pk_bf16_f32 v3, v0, v1
	global_store_dwordx2 v[34:35], v[2:3], off offset:112
	s_branch .LBB0_1035

.LBB0_1118:
	v_ashrrev_i32_e32 v14, 2, v1
	v_ashrrev_i32_e32 v68, 11, v1
	v_and_b32_e32 v19, 48, v17
	v_lshrrev_b32_e32 v2, 2, v1
	v_ashrrev_i32_e32 v15, 31, v14
	v_ashrrev_i32_e32 v69, 31, v68
	v_lshlrev_b32_e32 v20, 6, v14
	v_or_b32_e32 v21, v19, v0
	v_and_or_b32 v32, v2, s6, v4
	v_lshlrev_b64 v[14:15], 13, v[14:15]
	v_lshlrev_b64 v[60:61], 12, v[68:69]
	v_and_b32_e32 v20, 0xfc0, v20
	v_lshlrev_b32_e32 v2, 7, v21
	v_lshlrev_b32_e32 v94, 2, v32
	v_lshl_add_u64 v[28:29], s[58:59], 0, v[14:15]
	v_lshl_add_u64 v[30:31], s[60:61], 0, v[14:15]
	v_lshl_add_u64 v[14:15], v[6:7], 0, v[14:15]
	v_or3_b32 v19, v60, v20, v19
	global_load_dwordx4 v[20:23], v94, s[68:69]
	global_load_dwordx4 v[24:27], v94, s[70:71]
	global_load_dwordx4 v[96:99], v94, s[68:69] offset:64
	global_load_dwordx4 v[100:103], v94, s[70:71] offset:64
	global_load_dwordx4 v[104:107], v94, s[68:69] offset:128
	global_load_dwordx4 v[108:111], v94, s[70:71] offset:128
	global_load_dwordx4 v[112:115], v94, s[68:69] offset:192
	global_load_dwordx4 v[116:119], v94, s[70:71] offset:192
	v_lshl_add_u64 v[44:45], v[28:29], 0, v[2:3]
	v_lshl_add_u64 v[46:47], v[30:31], 0, v[2:3]
	v_lshlrev_b32_e32 v2, 1, v32
	global_load_dwordx4 v[28:31], v[14:15], off
	global_load_dwordx4 v[32:35], v[14:15], off offset:64
	global_load_dwordx4 v[36:39], v[14:15], off offset:2048
	global_load_dwordx4 v[40:43], v[14:15], off offset:2112
	v_add_co_u32_e32 v14, vcc, s8, v14
	v_or_b32_e32 v60, v19, v0
	s_nop 0
	v_addc_co_u32_e32 v15, vcc, 0, v15, vcc
	v_lshl_add_u64 v[64:65], v[44:45], 0, v[8:9]
	v_lshl_add_u64 v[66:67], v[46:47], 0, v[10:11]
	v_lshlrev_b64 v[70:71], 10, v[60:61]
	v_mad_u64_u32 v[72:73], s[12:13], v60, s7, v[12:13]
	global_load_dwordx4 v[44:47], v[14:15], off
	global_load_dwordx4 v[48:51], v[14:15], off offset:64
	global_load_dwordx4 v[52:55], v[14:15], off offset:2048
	global_load_dwordx4 v[56:59], v[14:15], off offset:2112
	v_lshlrev_b64 v[14:15], 11, v[60:61]
	global_load_dwordx2 v[74:75], v[66:67], off
	global_load_dwordx2 v[76:77], v[66:67], off offset:32
	global_load_dwordx4 v[60:63], v[64:65], off
	global_load_dwordx2 v[78:79], v[66:67], off offset:64
	global_load_dwordx2 v[80:81], v[66:67], off offset:96
	s_nop 0
	global_load_dwordx4 v[64:67], v[64:65], off offset:64
	v_lshl_add_u64 v[70:71], s[52:53], 0, v[70:71]
	v_mad_i32_i24 v73, v69, s7, v73
	v_lshl_add_u64 v[82:83], v[70:71], 0, v[2:3]
	v_lshl_add_u64 v[84:85], v[72:73], 0, v[2:3]
	global_load_dwordx2 v[86:87], v[82:83], off
	global_load_dwordx2 v[88:89], v[84:85], off offset:1024
	global_load_dwordx2 v[90:91], v[84:85], off offset:1056
	global_load_dwordx2 v[92:93], v[84:85], off offset:1088
	v_lshl_add_u64 v[14:15], s[22:23], 0, v[14:15]
	v_lshl_add_u64 v[14:15], v[14:15], 0, v[2:3]
	v_add_u32_e32 v1, s2, v1
	v_add_u32_e32 v17, s3, v17
	s_waitcnt vmcnt(9)
	v_lshlrev_b32_e32 v68, 16, v74
	v_and_b32_e32 v69, 0xffff0000, v74
	v_lshlrev_b32_e32 v70, 16, v75
	v_and_b32_e32 v71, 0xffff0000, v75
	s_waitcnt vmcnt(8)
	v_lshlrev_b32_e32 v72, 16, v76
	v_and_b32_e32 v73, 0xffff0000, v76
	v_lshlrev_b32_e32 v74, 16, v77
	v_and_b32_e32 v75, 0xffff0000, v77
	s_waitcnt vmcnt(7)
	v_mfma_f32_16x16x32_bf16 v[28:31], v[28:31], v[60:63], v[68:71]
	s_waitcnt vmcnt(3)
	v_lshlrev_b32_e32 v19, 16, v86
	v_and_b32_e32 v77, 0xffff0000, v87
	s_waitcnt vmcnt(2)
	v_lshlrev_b32_e32 v76, 16, v89
	v_mfma_f32_16x16x32_bf16 v[36:39], v[36:39], v[60:63], v[72:75]
	v_lshlrev_b32_e32 v68, 16, v78
	v_and_b32_e32 v69, 0xffff0000, v78
	v_lshlrev_b32_e32 v70, 16, v79
	v_and_b32_e32 v71, 0xffff0000, v79
	v_lshlrev_b32_e32 v72, 16, v80
	v_and_b32_e32 v73, 0xffff0000, v80
	v_lshlrev_b32_e32 v74, 16, v81
	v_and_b32_e32 v75, 0xffff0000, v81
	v_mfma_f32_16x16x32_bf16 v[44:47], v[44:47], v[60:63], v[68:71]
	v_and_b32_e32 v78, 0xffff0000, v89
	v_mfma_f32_16x16x32_bf16 v[52:55], v[52:55], v[60:63], v[72:75]
	global_load_dwordx2 v[60:61], v[82:83], off offset:32
	global_load_dwordx2 v[62:63], v[82:83], off offset:64
	global_load_dwordx2 v[68:69], v[82:83], off offset:96
	v_and_b32_e32 v73, 0xffff0000, v86
	v_lshlrev_b32_e32 v75, 16, v87
	v_mfma_f32_16x16x32_bf16 v[28:31], v[32:35], v[64:67], v[28:31]
	v_lshlrev_b32_e32 v72, 16, v88
	v_and_b32_e32 v74, 0xffff0000, v88
	global_load_dwordx2 v[70:71], v[84:85], off offset:1120
	v_mfma_f32_16x16x32_bf16 v[32:35], v[40:43], v[64:67], v[36:39]
	v_mfma_f32_16x16x32_bf16 v[36:39], v[48:51], v[64:67], v[44:47]
	s_nop 2
	v_mov_b32_e32 v48, v30
	s_nop 2
	v_mov_b32_e32 v49, v34
	v_mov_b32_e32 v50, v31
	v_mfma_f32_16x16x32_bf16 v[40:43], v[56:59], v[64:67], v[52:55]
	v_mov_b32_e32 v44, v28
	v_mov_b32_e32 v45, v32
	v_mov_b32_e32 v46, v29
	v_mov_b32_e32 v47, v33
	v_pk_add_f32 v[44:45], v[44:45], v[46:47]
	v_mov_b32_e32 v51, v35
	v_mov_b32_e32 v46, v36
	s_nop 0
	v_mov_b32_e32 v47, v40
	v_mov_b32_e32 v52, v37
	v_mov_b32_e32 v53, v41
	v_pk_add_f32 v[44:45], v[48:49], v[44:45]
	v_mov_b32_e32 v54, v38
	v_mov_b32_e32 v55, v42
	v_pk_add_f32 v[46:47], v[46:47], v[52:53]
	v_pk_add_f32 v[44:45], v[50:51], v[44:45]
	v_mov_b32_e32 v56, v39
	v_mov_b32_e32 v57, v43
	v_pk_add_f32 v[46:47], v[54:55], v[46:47]
	v_add_f32_e32 v2, 0, v44
	v_pk_add_f32 v[46:47], v[56:57], v[46:47]
	v_add_f32_e32 v2, v2, v45
	v_add_f32_e32 v2, v2, v46
	v_add_f32_e32 v2, v2, v47
	ds_bpermute_b32 v44, v5, v2
	s_waitcnt lgkmcnt(0)
	v_add_f32_e32 v2, v2, v44
	ds_bpermute_b32 v44, v16, v2
	s_waitcnt lgkmcnt(0)
	v_add_f32_e32 v44, v2, v44
	v_fmamk_f32 v49, v44, 0xbc800000, v29
	v_fmamk_f32 v48, v44, 0xbc800000, v28
	v_mul_f32_e32 v52, v49, v49
	v_fmamk_f32 v30, v44, 0xbc800000, v30
	v_fmac_f32_e32 v52, v48, v48
	v_fmac_f32_e32 v31, 0xbc800000, v44
	v_fmac_f32_e32 v52, v30, v30
	v_fmamk_f32 v50, v44, 0xbc800000, v32
	v_fmac_f32_e32 v52, v31, v31
	v_fmamk_f32 v51, v44, 0xbc800000, v33
	v_fmac_f32_e32 v52, v50, v50
	v_mul_f32_e32 v2, 0x3c800000, v44
	v_fmamk_f32 v34, v44, 0xbc800000, v34
	v_fmac_f32_e32 v52, v51, v51
	v_fmac_f32_e32 v35, 0xbc800000, v44
	v_pk_add_f32 v[28:29], v[36:37], v[2:3] op_sel_hi:[1,0] neg_lo:[0,1] neg_hi:[0,1]
	v_fmac_f32_e32 v52, v34, v34
	v_pk_add_f32 v[36:37], v[40:41], v[2:3] op_sel_hi:[1,0] neg_lo:[0,1] neg_hi:[0,1]
	v_pk_mul_f32 v[40:41], v[28:29], v[28:29]
	v_fmac_f32_e32 v52, v35, v35
	v_pk_add_f32 v[32:33], v[38:39], v[2:3] op_sel_hi:[1,0] neg_lo:[0,1] neg_hi:[0,1]
	v_pk_add_f32 v[38:39], v[42:43], v[2:3] op_sel_hi:[1,0] neg_lo:[0,1] neg_hi:[0,1]
	v_add_f32_e32 v2, v40, v52
	v_pk_mul_f32 v[42:43], v[32:33], v[32:33]
	v_add_f32_e32 v2, v41, v2
	v_add_f32_e32 v2, v42, v2
	v_pk_mul_f32 v[44:45], v[36:37], v[36:37]
	v_add_f32_e32 v2, v43, v2
	v_add_f32_e32 v2, v44, v2
	v_pk_mul_f32 v[46:47], v[38:39], v[38:39]
	v_add_f32_e32 v2, v45, v2
	v_add_f32_e32 v2, v46, v2
	v_add_f32_e32 v2, v47, v2
	ds_bpermute_b32 v40, v5, v2
	s_waitcnt vmcnt(3)
	v_and_b32_e32 v43, 0xffff0000, v61
	v_lshlrev_b32_e32 v42, 16, v91
	v_and_b32_e32 v44, 0xffff0000, v91
	s_waitcnt lgkmcnt(0)
	v_add_f32_e32 v2, v2, v40
	ds_bpermute_b32 v40, v16, v2
	s_waitcnt lgkmcnt(0)
	v_add_f32_e32 v2, v2, v40
	v_fmamk_f32 v2, v2, 0x3c800000, v18
	v_mul_f32_e32 v40, 0x4b800000, v2
	v_cmp_gt_f32_e32 vcc, s9, v2
	s_nop 1
	v_cndmask_b32_e32 v2, v2, v40, vcc
	v_rsq_f32_e32 v2, v2
	s_nop 0
	v_mul_f32_e32 v40, 0x45800000, v2
	v_cndmask_b32_e32 v2, v2, v40, vcc
	v_mul_f32_e32 v40, v48, v2
	v_mul_f32_e32 v41, v49, v2
	v_mul_f32_e32 v30, v30, v2
	v_mul_f32_e32 v31, v31, v2
	v_fma_f32 v20, v20, v40, v24
	v_fma_f32 v21, v21, v41, v25
	v_fma_f32 v22, v22, v30, v26
	v_fmac_f32_e32 v27, v23, v31
	v_add_f32_e32 v19, v20, v19
	v_add_f32_e32 v20, v21, v73
	v_add_f32_e32 v21, v22, v75
	v_add_f32_e32 v22, v27, v77
	v_mul_f32_e32 v19, v19, v72
	v_mul_f32_e32 v20, v20, v74
	v_mul_f32_e32 v21, v21, v76
	v_mul_f32_e32 v22, v22, v78
	v_cvt_pk_bf16_f32 v20, v19, v20
	v_cvt_pk_bf16_f32 v21, v21, v22
	global_store_dwordx2 v[14:15], v[20:21], off offset:1024
	v_mul_f32_e32 v45, v50, v2
	v_mul_f32_e32 v46, v51, v2
	v_mul_f32_e32 v34, v34, v2
	v_mul_f32_e32 v35, v35, v2
	v_lshlrev_b32_e32 v19, 16, v60
	v_and_b32_e32 v31, 0xffff0000, v60
	v_lshlrev_b32_e32 v41, 16, v61
	v_lshlrev_b32_e32 v30, 16, v90
	v_and_b32_e32 v40, 0xffff0000, v90
	v_mul_f32_e32 v28, v28, v2
	v_mul_f32_e32 v29, v29, v2
	v_mul_f32_e32 v32, v32, v2
	v_mul_f32_e32 v33, v33, v2
	v_cmp_lt_i32_e32 vcc, s10, v1
	s_or_b64 s[4:5], vcc, s[4:5]
	s_waitcnt vmcnt(1)
	v_mov_b32_e32 v20, v96
	v_mov_b32_e32 v21, v97
	v_mov_b32_e32 v22, v98
	v_mov_b32_e32 v23, v99
	v_mov_b32_e32 v24, v100
	v_mov_b32_e32 v25, v101
	v_mov_b32_e32 v26, v102
	v_mov_b32_e32 v27, v103
	v_fma_f32 v20, v20, v45, v24
	v_fma_f32 v21, v21, v46, v25
	v_fma_f32 v22, v22, v34, v26
	v_fmac_f32_e32 v27, v23, v35
	v_add_f32_e32 v19, v20, v19
	v_add_f32_e32 v20, v21, v31
	v_add_f32_e32 v21, v22, v41
	v_add_f32_e32 v22, v27, v43
	v_mul_f32_e32 v19, v19, v30
	v_mul_f32_e32 v20, v20, v40
	v_mul_f32_e32 v21, v21, v42
	v_mul_f32_e32 v22, v22, v44
	v_cvt_pk_bf16_f32 v20, v19, v20
	v_cvt_pk_bf16_f32 v21, v21, v22
	global_store_dwordx2 v[14:15], v[20:21], off offset:1056
	v_lshlrev_b32_e32 v19, 16, v62
	v_and_b32_e32 v31, 0xffff0000, v62
	v_lshlrev_b32_e32 v35, 16, v63
	v_and_b32_e32 v41, 0xffff0000, v63
	v_lshlrev_b32_e32 v30, 16, v92
	v_and_b32_e32 v34, 0xffff0000, v92
	v_lshlrev_b32_e32 v40, 16, v93
	v_and_b32_e32 v42, 0xffff0000, v93
	s_waitcnt vmcnt(2)
	v_mov_b32_e32 v20, v104
	v_mov_b32_e32 v21, v105
	v_mov_b32_e32 v22, v106
	v_mov_b32_e32 v23, v107
	v_mov_b32_e32 v24, v108
	v_mov_b32_e32 v25, v109
	v_mov_b32_e32 v26, v110
	v_mov_b32_e32 v27, v111
	v_fma_f32 v20, v20, v28, v24
	v_fma_f32 v21, v21, v29, v25
	v_fma_f32 v22, v22, v32, v26
	v_fmac_f32_e32 v27, v23, v33
	v_add_f32_e32 v19, v20, v19
	v_add_f32_e32 v20, v21, v31
	v_add_f32_e32 v21, v22, v35
	v_add_f32_e32 v22, v27, v41
	v_mul_f32_e32 v19, v19, v30
	v_mul_f32_e32 v20, v20, v34
	v_mul_f32_e32 v21, v21, v40
	v_mul_f32_e32 v22, v22, v42
	v_cvt_pk_bf16_f32 v20, v19, v20
	v_cvt_pk_bf16_f32 v21, v21, v22
	global_store_dwordx2 v[14:15], v[20:21], off offset:1088
	v_mul_f32_e32 v35, v36, v2
	v_mul_f32_e32 v36, v37, v2
	v_mul_f32_e32 v37, v38, v2
	v_mul_f32_e32 v2, v39, v2
	v_lshlrev_b32_e32 v19, 16, v68
	v_and_b32_e32 v29, 0xffff0000, v68
	v_lshlrev_b32_e32 v31, 16, v69
	v_and_b32_e32 v33, 0xffff0000, v69
	v_lshlrev_b32_e32 v28, 16, v70
	v_and_b32_e32 v30, 0xffff0000, v70
	v_lshlrev_b32_e32 v32, 16, v71
	v_and_b32_e32 v34, 0xffff0000, v71
	s_waitcnt vmcnt(3)
	v_mov_b32_e32 v20, v112
	v_mov_b32_e32 v21, v113
	v_mov_b32_e32 v22, v114
	v_mov_b32_e32 v23, v115
	v_mov_b32_e32 v24, v116
	v_mov_b32_e32 v25, v117
	v_mov_b32_e32 v26, v118
	v_mov_b32_e32 v27, v119
	v_fma_f32 v20, v20, v35, v24
	v_fma_f32 v21, v36, v21, v25
	v_fma_f32 v22, v37, v22, v26
	v_fmac_f32_e32 v27, v2, v23
	v_add_f32_e32 v2, v20, v19
	v_add_f32_e32 v19, v21, v29
	v_add_f32_e32 v20, v22, v31
	v_add_f32_e32 v21, v27, v33
	v_mul_f32_e32 v2, v2, v28
	v_mul_f32_e32 v19, v19, v30
	v_mul_f32_e32 v22, v20, v32
	v_mul_f32_e32 v21, v21, v34
	v_cvt_pk_bf16_f32 v20, v2, v19
	v_cvt_pk_bf16_f32 v21, v22, v21
	global_store_dwordx2 v[14:15], v[20:21], off offset:1120
	s_andn2_b64 exec, exec, s[4:5]
	s_cbranch_execnz .LBB0_1118

.LBB0_1317:
	s_or_b64 exec, exec, s[0:1]
	s_waitcnt lgkmcnt(0)
	v_mov_b32_e32 v0, v174
	s_barrier
	v_readlane_b32 s0, v240, 17
	v_ashrrev_i32_e32 v1, 5, v174
	v_and_b32_e32 v1, -2, v1
	v_add_u32_e32 v8, s0, v1
	s_mov_b32 s0, 0x8000
	v_cmp_gt_i32_e32 vcc, s0, v8
	s_and_saveexec_b64 s[0:1], vcc
	s_cbranch_execz .LBB0_1320
	v_and_b32_e32 v1, 64, v175
	v_add_u32_e32 v1, 64, v1
	v_xor_b32_e32 v3, 32, v175
	v_cmp_lt_i32_e32 vcc, v3, v1
	v_and_b32_e32 v0, 63, v0
	v_mov_b32_e32 v11, 0
	v_cndmask_b32_e32 v3, v175, v3, vcc
	v_lshlrev_b32_e32 v29, 2, v3
	v_xor_b32_e32 v3, 16, v175
	v_cmp_lt_i32_e32 vcc, v3, v1
	v_readlane_b32 s36, v241, 17
	v_or_b32_e32 v2, 64, v0
	v_cndmask_b32_e32 v3, v175, v3, vcc
	v_lshlrev_b32_e32 v34, 2, v3
	v_xor_b32_e32 v3, 8, v175
	v_cmp_lt_i32_e32 vcc, v3, v1
	v_or_b32_e32 v4, 0x80, v0
	v_or_b32_e32 v6, 0xc0, v0
	v_cndmask_b32_e32 v3, v175, v3, vcc
	v_lshlrev_b32_e32 v35, 2, v3
	v_xor_b32_e32 v3, 4, v175
	v_cmp_lt_i32_e32 vcc, v3, v1
	v_lshlrev_b32_e32 v10, 4, v0
	v_readlane_b32 s37, v241, 18
	v_cndmask_b32_e32 v3, v175, v3, vcc
	v_lshlrev_b32_e32 v36, 2, v3
	v_xor_b32_e32 v3, 2, v175
	v_cmp_lt_i32_e32 vcc, v3, v1
	v_lshlrev_b32_e32 v18, 3, v0
	v_mov_b32_e32 v19, v11
	v_cndmask_b32_e32 v3, v175, v3, vcc
	v_lshlrev_b32_e32 v37, 2, v3
	v_xor_b32_e32 v3, 1, v175
	v_cmp_lt_i32_e32 vcc, v3, v1
	s_lshl_b32 s5, s88, 4
	v_lshl_add_u64 v[12:13], s[30:31], 0, v[10:11]
	v_cndmask_b32_e32 v1, v175, v3, vcc
	v_lshlrev_b32_e32 v38, 2, v1
	v_lshl_add_u64 v[14:15], s[16:17], 0, v[10:11]
	v_lshl_add_u64 v[16:17], s[36:37], 0, v[10:11]
	v_lshl_add_u64 v[18:19], s[66:67], 0, v[18:19]
	v_lshl_add_u64 v[20:21], s[18:19], 0, v[10:11]
	s_mov_b64 s[0:1], 0
	s_mov_b64 s[2:3], 0x2000
	v_lshlrev_b32_e32 v10, 4, v0
	v_lshlrev_b32_e32 v22, 4, v2
	v_mov_b32_e32 v23, v11
	v_lshlrev_b32_e32 v24, 4, v4
	v_mov_b32_e32 v25, v11
	v_lshlrev_b32_e32 v26, 4, v6
	v_mov_b32_e32 v27, v11
	s_mov_b32 s4, 0x3f9837f0
	s_mov_b32 s6, 0x3a800000
	v_mov_b32_e32 v28, 0x3727c5ac
	s_mov_b32 s7, 0x800000
	s_movk_i32 s8, 0x7fff
	v_readlane_b32 s38, v241, 19
	v_readlane_b32 s39, v241, 20
	v_readlane_b32 s40, v241, 21
	v_readlane_b32 s41, v241, 22
	v_readlane_b32 s42, v241, 23
	v_readlane_b32 s43, v241, 24
	v_readlane_b32 s44, v241, 25
	v_readlane_b32 s45, v241, 26
	v_readlane_b32 s46, v241, 27
	v_readlane_b32 s47, v241, 28
	v_readlane_b32 s48, v241, 29
	v_readlane_b32 s49, v241, 30
	v_readlane_b32 s50, v241, 31
	v_readlane_b32 s51, v241, 32
	global_load_dwordx4 v[176:179], v[12:13], off
	global_load_dwordx4 v[180:183], v[12:13], off offset:1024
	global_load_dwordx4 v[184:187], v[12:13], off offset:2048
	global_load_dwordx4 v[188:191], v[12:13], off offset:3072
	global_load_dwordx4 v[192:195], v[14:15], off
	global_load_dwordx4 v[196:199], v[14:15], off offset:1024
	global_load_dwordx4 v[200:203], v[14:15], off offset:2048
	global_load_dwordx4 v[204:207], v[14:15], off offset:3072
	s_waitcnt vmcnt(0)
.LBB0_1319:
	v_ashrrev_i32_e32 v30, 12, v8
	v_mul_i32_i24_e32 v40, 0xc00, v30
	v_ashrrev_i32_e32 v9, 31, v8
	v_add_u32_e32 v32, 1, v8
	v_ashrrev_i32_e32 v41, 31, v40
	v_lshlrev_b64 v[30:31], 11, v[8:9]
	v_ashrrev_i32_e32 v33, 31, v32
	v_lshl_add_u64 v[58:59], v[40:41], 2, s[20:21]
	v_lshlrev_b64 v[42:43], 12, v[8:9]
	v_lshl_add_u64 v[44:45], v[18:19], 0, v[30:31]
	v_lshlrev_b64 v[30:31], 12, v[32:33]
	v_lshlrev_b64 v[46:47], 11, v[32:33]
	v_lshl_add_u64 v[76:77], v[58:59], 0, s[2:3]
	v_lshl_add_u64 v[56:57], v[16:17], 0, v[42:43]
	v_lshl_add_u64 v[72:73], v[16:17], 0, v[30:31]
	v_lshl_add_u64 v[74:75], v[18:19], 0, v[46:47]
	v_lshl_add_u64 v[104:105], v[76:77], 0, v[10:11]
	v_mov_b32_e32 v0, v176
	v_mov_b32_e32 v1, v177
	v_mov_b32_e32 v2, v178
	v_mov_b32_e32 v3, v179
	v_mov_b32_e32 v4, v192
	v_mov_b32_e32 v5, v193
	v_mov_b32_e32 v6, v194
	v_mov_b32_e32 v7, v195
	v_lshl_add_u64 v[32:33], v[20:21], 0, v[42:43]
	global_load_dwordx2 v[88:89], v[44:45], off
	global_load_dwordx2 v[90:91], v[44:45], off offset:512
	global_load_dwordx2 v[92:93], v[44:45], off offset:1024
	global_load_dwordx2 v[94:95], v[44:45], off offset:1536
	global_load_dwordx4 v[40:43], v[56:57], off
	s_nop 0
	global_load_dwordx4 v[44:47], v[56:57], off offset:1024
	global_load_dwordx4 v[48:51], v[56:57], off offset:2048
	global_load_dwordx4 v[52:55], v[56:57], off offset:3072
	global_load_dwordx2 v[96:97], v[74:75], off
	global_load_dwordx2 v[98:99], v[74:75], off offset:512
	global_load_dwordx2 v[100:101], v[74:75], off offset:1024
	global_load_dwordx2 v[102:103], v[74:75], off offset:1536
	s_nop 0
	global_load_dwordx4 v[56:59], v[72:73], off
	global_load_dwordx4 v[60:63], v[72:73], off offset:1024
	global_load_dwordx4 v[64:67], v[72:73], off offset:2048
	global_load_dwordx4 v[68:71], v[72:73], off offset:3072
	v_lshl_add_u64 v[106:107], v[76:77], 0, v[22:23]
	v_lshl_add_u64 v[108:109], v[76:77], 0, v[24:25]
	v_lshl_add_u64 v[110:111], v[76:77], 0, v[26:27]
	global_load_dwordx4 v[72:75], v[104:105], off
	global_load_dwordx4 v[76:79], v[106:107], off
	global_load_dwordx4 v[80:83], v[108:109], off
	global_load_dwordx4 v[84:87], v[110:111], off
	v_lshl_add_u64 v[30:31], v[20:21], 0, v[30:31]
	v_add_u32_e32 v8, s5, v8
	s_waitcnt vmcnt(9)
	v_lshlrev_b32_e32 v116, 16, v100
	v_lshlrev_b32_e32 v104, 16, v88
	v_and_b32_e32 v105, 0xffff0000, v88
	v_lshlrev_b32_e32 v106, 16, v90
	v_and_b32_e32 v107, 0xffff0000, v90
	v_lshlrev_b32_e32 v112, 16, v96
	v_and_b32_e32 v113, 0xffff0000, v96
	v_lshlrev_b32_e32 v114, 16, v98
	v_and_b32_e32 v115, 0xffff0000, v98
	v_and_b32_e32 v117, 0xffff0000, v100
	s_waitcnt vmcnt(8)
	v_lshlrev_b32_e32 v118, 16, v102
	v_and_b32_e32 v119, 0xffff0000, v102
	s_waitcnt vmcnt(3)
	v_pk_add_f32 v[72:73], v[72:73], 1.0 op_sel_hi:[1,0]
	s_waitcnt vmcnt(2)
	v_pk_add_f32 v[76:77], v[76:77], 1.0 op_sel_hi:[1,0]
	s_waitcnt vmcnt(1)
	v_pk_add_f32 v[80:81], v[80:81], 1.0 op_sel_hi:[1,0]
	s_waitcnt vmcnt(0)
	v_pk_add_f32 v[84:85], v[84:85], 1.0 op_sel_hi:[1,0]
	v_lshlrev_b32_e32 v88, 16, v89
	v_and_b32_e32 v89, 0xffff0000, v89
	v_lshlrev_b32_e32 v90, 16, v91
	v_and_b32_e32 v91, 0xffff0000, v91
	v_lshlrev_b32_e32 v108, 16, v92
	v_and_b32_e32 v109, 0xffff0000, v92
	v_lshlrev_b32_e32 v92, 16, v93
	v_and_b32_e32 v93, 0xffff0000, v93
	v_lshlrev_b32_e32 v96, 16, v97
	v_and_b32_e32 v97, 0xffff0000, v97
	v_lshlrev_b32_e32 v98, 16, v99
	v_and_b32_e32 v99, 0xffff0000, v99
	v_lshlrev_b32_e32 v100, 16, v101
	v_and_b32_e32 v101, 0xffff0000, v101
	v_pk_add_f32 v[74:75], v[74:75], 1.0 op_sel_hi:[1,0]
	v_pk_add_f32 v[78:79], v[78:79], 1.0 op_sel_hi:[1,0]
	v_pk_add_f32 v[82:83], v[82:83], 1.0 op_sel_hi:[1,0]
	v_pk_mul_f32 v[112:113], v[72:73], v[112:113]
	v_pk_mul_f32 v[114:115], v[76:77], v[114:115]
	v_pk_mul_f32 v[116:117], v[80:81], v[116:117]
	v_pk_mul_f32 v[118:119], v[84:85], v[118:119]
	v_pk_mul_f32 v[72:73], v[72:73], v[104:105]
	v_pk_mul_f32 v[76:77], v[76:77], v[106:107]
	v_lshlrev_b32_e32 v110, 16, v94
	v_and_b32_e32 v111, 0xffff0000, v94
	v_pk_mul_f32 v[96:97], v[74:75], v[96:97]
	v_pk_mul_f32 v[98:99], v[78:79], v[98:99]
	v_pk_mul_f32 v[100:101], v[82:83], v[100:101]
	v_pk_mul_f32 v[74:75], v[74:75], v[88:89]
	v_pk_mul_f32 v[78:79], v[78:79], v[90:91]
	v_pk_mul_f32 v[80:81], v[80:81], v[108:109]
	v_pk_mul_f32 v[82:83], v[82:83], v[92:93]
	v_pk_fma_f32 v[56:57], v[56:57], s[4:5], v[112:113] op_sel_hi:[1,0,1]
	v_pk_fma_f32 v[60:61], v[60:61], s[4:5], v[114:115] op_sel_hi:[1,0,1]
	v_pk_fma_f32 v[64:65], v[64:65], s[4:5], v[116:117] op_sel_hi:[1,0,1]
	v_pk_fma_f32 v[68:69], v[68:69], s[4:5], v[118:119] op_sel_hi:[1,0,1]
	v_pk_fma_f32 v[40:41], v[40:41], s[4:5], v[72:73] op_sel_hi:[1,0,1]
	v_pk_fma_f32 v[44:45], v[44:45], s[4:5], v[76:77] op_sel_hi:[1,0,1]
	v_lshlrev_b32_e32 v94, 16, v95
	v_and_b32_e32 v95, 0xffff0000, v95
	v_lshlrev_b32_e32 v102, 16, v103
	v_and_b32_e32 v103, 0xffff0000, v103
	v_pk_add_f32 v[86:87], v[86:87], 1.0 op_sel_hi:[1,0]
	v_pk_mul_f32 v[84:85], v[84:85], v[110:111]
	v_pk_fma_f32 v[58:59], v[58:59], s[4:5], v[96:97] op_sel_hi:[1,0,1]
	v_pk_fma_f32 v[62:63], v[62:63], s[4:5], v[98:99] op_sel_hi:[1,0,1]
	v_pk_fma_f32 v[42:43], v[42:43], s[4:5], v[74:75] op_sel_hi:[1,0,1]
	v_pk_fma_f32 v[46:47], v[46:47], s[4:5], v[78:79] op_sel_hi:[1,0,1]
	v_pk_fma_f32 v[48:49], v[48:49], s[4:5], v[80:81] op_sel_hi:[1,0,1]
	v_pk_fma_f32 v[50:51], v[50:51], s[4:5], v[82:83] op_sel_hi:[1,0,1]
	v_mov_b32_e32 v72, v56
	v_mov_b32_e32 v73, v60
	v_mov_b32_e32 v74, v57
	v_mov_b32_e32 v75, v61
	v_mov_b32_e32 v80, v64
	v_mov_b32_e32 v81, v68
	v_mov_b32_e32 v82, v65
	v_mov_b32_e32 v83, v69
	v_mov_b32_e32 v88, v40
	v_mov_b32_e32 v89, v44
	v_mov_b32_e32 v90, v41
	v_mov_b32_e32 v91, v45
	v_pk_mul_f32 v[102:103], v[86:87], v[102:103]
	v_pk_mul_f32 v[86:87], v[86:87], v[94:95]
	v_pk_fma_f32 v[52:53], v[52:53], s[4:5], v[84:85] op_sel_hi:[1,0,1]
	v_mov_b32_e32 v76, v58
	v_mov_b32_e32 v77, v62
	v_mov_b32_e32 v92, v42
	v_mov_b32_e32 v93, v46
	v_pk_add_f32 v[72:73], v[72:73], v[74:75]
	v_pk_add_f32 v[74:75], v[80:81], v[82:83]
	v_pk_add_f32 v[80:81], v[88:89], v[90:91]
	v_pk_fma_f32 v[66:67], v[66:67], s[4:5], v[100:101] op_sel_hi:[1,0,1]
	v_pk_fma_f32 v[70:71], v[70:71], s[4:5], v[102:103] op_sel_hi:[1,0,1]
	v_pk_fma_f32 v[54:55], v[54:55], s[4:5], v[86:87] op_sel_hi:[1,0,1]
	v_mov_b32_e32 v78, v59
	v_mov_b32_e32 v79, v63
	v_mov_b32_e32 v94, v43
	v_mov_b32_e32 v95, v47
	v_mov_b32_e32 v96, v48
	v_mov_b32_e32 v97, v52
	v_mov_b32_e32 v98, v49
	v_mov_b32_e32 v99, v53
	v_pk_add_f32 v[72:73], v[72:73], v[76:77]
	v_pk_add_f32 v[76:77], v[80:81], v[92:93]
	v_mov_b32_e32 v84, v66
	v_mov_b32_e32 v85, v70
	v_mov_b32_e32 v100, v50
	v_mov_b32_e32 v101, v54
	v_pk_add_f32 v[82:83], v[96:97], v[98:99]
	v_pk_add_f32 v[72:73], v[78:79], v[72:73]
	v_pk_add_f32 v[76:77], v[76:77], v[94:95]
	v_mov_b32_e32 v86, v67
	v_mov_b32_e32 v87, v71
	v_mov_b32_e32 v102, v51
	v_mov_b32_e32 v103, v55
	v_pk_add_f32 v[74:75], v[74:75], v[84:85]
	v_pk_add_f32 v[80:81], v[82:83], v[100:101]
	v_add_f32_e32 v9, 0, v72
	v_add_f32_e32 v39, 0, v76
	v_pk_add_f32 v[74:75], v[86:87], v[74:75]
	v_pk_add_f32 v[78:79], v[80:81], v[102:103]
	v_add_f32_e32 v9, v9, v73
	v_add_f32_e32 v39, v39, v77
	v_add_f32_e32 v9, v9, v74
	v_add_f32_e32 v39, v39, v78
	v_add_f32_e32 v39, v39, v79
	v_add_f32_e32 v9, v9, v75
	ds_bpermute_b32 v72, v29, v39
	ds_bpermute_b32 v73, v29, v9
	s_waitcnt lgkmcnt(1)
	v_add_f32_e32 v39, v39, v72
	s_waitcnt lgkmcnt(0)
	v_add_f32_e32 v9, v9, v73
	ds_bpermute_b32 v72, v34, v39
	ds_bpermute_b32 v73, v34, v9
	s_waitcnt lgkmcnt(1)
	v_add_f32_e32 v39, v39, v72
	s_waitcnt lgkmcnt(0)
	v_add_f32_e32 v9, v9, v73
	ds_bpermute_b32 v72, v35, v39
	ds_bpermute_b32 v73, v35, v9
	s_waitcnt lgkmcnt(1)
	v_add_f32_e32 v39, v39, v72
	s_waitcnt lgkmcnt(0)
	v_add_f32_e32 v9, v9, v73
	ds_bpermute_b32 v72, v36, v39
	ds_bpermute_b32 v73, v36, v9
	s_waitcnt lgkmcnt(1)
	v_add_f32_e32 v39, v39, v72
	s_waitcnt lgkmcnt(0)
	v_add_f32_e32 v9, v9, v73
	ds_bpermute_b32 v72, v37, v39
	ds_bpermute_b32 v73, v37, v9
	s_waitcnt lgkmcnt(1)
	v_add_f32_e32 v39, v39, v72
	s_waitcnt lgkmcnt(0)
	v_add_f32_e32 v9, v9, v73
	ds_bpermute_b32 v72, v38, v39
	ds_bpermute_b32 v73, v38, v9
	s_waitcnt lgkmcnt(1)
	v_add_f32_e32 v39, v39, v72
	s_waitcnt lgkmcnt(0)
	v_add_f32_e32 v9, v9, v73
	v_mul_f32_e32 v72, 0x3a800000, v39
	v_mul_f32_e32 v74, 0x3a800000, v9
	v_pk_add_f32 v[40:41], v[40:41], v[72:73] op_sel_hi:[1,0] neg_lo:[0,1] neg_hi:[0,1]
	v_pk_add_f32 v[44:45], v[44:45], v[72:73] op_sel_hi:[1,0] neg_lo:[0,1] neg_hi:[0,1]
	v_pk_add_f32 v[48:49], v[48:49], v[72:73] op_sel_hi:[1,0] neg_lo:[0,1] neg_hi:[0,1]
	v_pk_add_f32 v[52:53], v[52:53], v[72:73] op_sel_hi:[1,0] neg_lo:[0,1] neg_hi:[0,1]
	v_pk_add_f32 v[56:57], v[56:57], v[74:75] op_sel_hi:[1,0] neg_lo:[0,1] neg_hi:[0,1]
	v_pk_add_f32 v[60:61], v[60:61], v[74:75] op_sel_hi:[1,0] neg_lo:[0,1] neg_hi:[0,1]
	v_pk_add_f32 v[58:59], v[58:59], v[74:75] op_sel_hi:[1,0] neg_lo:[0,1] neg_hi:[0,1]
	v_pk_add_f32 v[62:63], v[62:63], v[74:75] op_sel_hi:[1,0] neg_lo:[0,1] neg_hi:[0,1]
	v_pk_add_f32 v[64:65], v[64:65], v[74:75] op_sel_hi:[1,0] neg_lo:[0,1] neg_hi:[0,1]
	v_pk_add_f32 v[66:67], v[66:67], v[74:75] op_sel_hi:[1,0] neg_lo:[0,1] neg_hi:[0,1]
	v_pk_add_f32 v[68:69], v[68:69], v[74:75] op_sel_hi:[1,0] neg_lo:[0,1] neg_hi:[0,1]
	v_pk_add_f32 v[70:71], v[70:71], v[74:75] op_sel_hi:[1,0] neg_lo:[0,1] neg_hi:[0,1]
	v_mov_b32_e32 v74, v41
	v_mov_b32_e32 v75, v45
	v_mov_b32_e32 v82, v53
	v_mov_b32_e32 v83, v49
	v_mov_b32_e32 v90, v57
	v_mov_b32_e32 v91, v61
	v_pk_add_f32 v[42:43], v[42:43], v[72:73] op_sel_hi:[1,0] neg_lo:[0,1] neg_hi:[0,1]
	v_pk_add_f32 v[46:47], v[46:47], v[72:73] op_sel_hi:[1,0] neg_lo:[0,1] neg_hi:[0,1]
	v_pk_add_f32 v[50:51], v[50:51], v[72:73] op_sel_hi:[1,0] neg_lo:[0,1] neg_hi:[0,1]
	v_pk_add_f32 v[54:55], v[54:55], v[72:73] op_sel_hi:[1,0] neg_lo:[0,1] neg_hi:[0,1]
	v_mov_b32_e32 v72, v40
	v_mov_b32_e32 v73, v44
	v_mov_b32_e32 v80, v52
	v_mov_b32_e32 v81, v48
	v_mov_b32_e32 v88, v56
	v_mov_b32_e32 v89, v60
	v_mov_b32_e32 v98, v69
	v_mov_b32_e32 v99, v65
	v_pk_mul_f32 v[74:75], v[74:75], v[74:75]
	v_pk_mul_f32 v[82:83], v[82:83], v[82:83]
	v_pk_mul_f32 v[90:91], v[90:91], v[90:91]
	v_mov_b32_e32 v76, v42
	v_mov_b32_e32 v77, v46
	v_mov_b32_e32 v92, v58
	v_mov_b32_e32 v93, v62
	v_mov_b32_e32 v96, v68
	v_mov_b32_e32 v97, v64
	v_pk_mul_f32 v[98:99], v[98:99], v[98:99]
	v_pk_fma_f32 v[72:73], v[72:73], v[72:73], v[74:75]
	v_pk_fma_f32 v[74:75], v[80:81], v[80:81], v[82:83]
	v_pk_fma_f32 v[80:81], v[88:89], v[88:89], v[90:91]
	v_mov_b32_e32 v78, v43
	v_mov_b32_e32 v79, v47
	v_mov_b32_e32 v84, v54
	v_mov_b32_e32 v85, v50
	v_mov_b32_e32 v94, v59
	v_mov_b32_e32 v95, v63
	v_mov_b32_e32 v100, v70
	v_mov_b32_e32 v101, v66
	v_pk_fma_f32 v[82:83], v[96:97], v[96:97], v[98:99]
	v_pk_fma_f32 v[72:73], v[76:77], v[76:77], v[72:73]
	v_pk_fma_f32 v[76:77], v[92:93], v[92:93], v[80:81]
	v_mov_b32_e32 v86, v55
	v_mov_b32_e32 v87, v51
	v_mov_b32_e32 v102, v71
	v_mov_b32_e32 v103, v67
	v_pk_fma_f32 v[74:75], v[84:85], v[84:85], v[74:75]
	v_pk_fma_f32 v[80:81], v[100:101], v[100:101], v[82:83]
	v_pk_fma_f32 v[72:73], v[78:79], v[78:79], v[72:73]
	v_pk_fma_f32 v[76:77], v[94:95], v[94:95], v[76:77]
	v_pk_fma_f32 v[74:75], v[86:87], v[86:87], v[74:75]
	v_pk_fma_f32 v[78:79], v[102:103], v[102:103], v[80:81]
	v_mov_b32_e32 v80, v76
	v_mov_b32_e32 v81, v72
	v_mov_b32_e32 v72, v77
	v_mov_b32_e32 v76, v79
	v_mov_b32_e32 v77, v75
	v_pk_add_f32 v[72:73], v[80:81], v[72:73]
	v_mov_b32_e32 v79, v74
	v_pk_add_f32 v[72:73], v[76:77], v[72:73]
	s_nop 0
	v_pk_add_f32 v[72:73], v[78:79], v[72:73]
	ds_bpermute_b32 v75, v29, v73
	ds_bpermute_b32 v74, v29, v72
	s_waitcnt lgkmcnt(0)
	v_pk_add_f32 v[72:73], v[72:73], v[74:75]
	ds_bpermute_b32 v75, v34, v73
	ds_bpermute_b32 v74, v34, v72
	s_waitcnt lgkmcnt(0)
	v_pk_add_f32 v[72:73], v[72:73], v[74:75]
	ds_bpermute_b32 v75, v35, v73
	ds_bpermute_b32 v74, v35, v72
	s_waitcnt lgkmcnt(0)
	v_pk_add_f32 v[72:73], v[72:73], v[74:75]
	ds_bpermute_b32 v75, v36, v73
	ds_bpermute_b32 v74, v36, v72
	s_waitcnt lgkmcnt(0)
	v_pk_add_f32 v[72:73], v[72:73], v[74:75]
	ds_bpermute_b32 v75, v37, v73
	ds_bpermute_b32 v74, v37, v72
	s_waitcnt lgkmcnt(0)
	v_pk_add_f32 v[72:73], v[72:73], v[74:75]
	ds_bpermute_b32 v75, v38, v73
	ds_bpermute_b32 v74, v38, v72
	s_waitcnt lgkmcnt(0)
	v_pk_add_f32 v[72:73], v[72:73], v[74:75]
	s_nop 0
	v_pk_fma_f32 v[72:73], v[72:73], s[6:7], v[28:29] op_sel_hi:[1,0,0]
	s_nop 0
	v_mul_f32_e32 v9, 0x4b800000, v73
	v_cmp_gt_f32_e32 vcc, s7, v73
	s_nop 1
	v_cndmask_b32_e32 v9, v73, v9, vcc
	v_rsq_f32_e32 v9, v9
	s_nop 0
	v_mul_f32_e32 v39, 0x45800000, v9
	v_cndmask_b32_e32 v74, v9, v39, vcc
	v_pk_mul_f32 v[40:41], v[40:41], v[74:75] op_sel_hi:[1,0]
	v_pk_mul_f32 v[42:43], v[42:43], v[74:75] op_sel_hi:[1,0]
	v_pk_fma_f32 v[0:1], v[0:1], v[40:41], v[4:5]
	v_pk_fma_f32 v[2:3], v[2:3], v[42:43], v[6:7]
	global_store_dwordx4 v[32:33], v[0:3], off
	v_pk_mul_f32 v[40:41], v[44:45], v[74:75] op_sel_hi:[1,0]
	v_pk_mul_f32 v[42:43], v[46:47], v[74:75] op_sel_hi:[1,0]
	v_mul_f32_e32 v9, 0x4b800000, v72
	v_cmp_gt_f32_e32 vcc, s7, v72
	v_mov_b32_e32 v0, v180
	v_mov_b32_e32 v1, v181
	v_mov_b32_e32 v2, v182
	v_mov_b32_e32 v3, v183
	v_mov_b32_e32 v4, v196
	v_mov_b32_e32 v5, v197
	v_mov_b32_e32 v6, v198
	v_mov_b32_e32 v7, v199
	v_pk_fma_f32 v[0:1], v[0:1], v[40:41], v[4:5]
	v_pk_fma_f32 v[2:3], v[2:3], v[42:43], v[6:7]
	global_store_dwordx4 v[32:33], v[0:3], off offset:1024
	v_pk_mul_f32 v[40:41], v[48:49], v[74:75] op_sel_hi:[1,0]
	v_pk_mul_f32 v[42:43], v[50:51], v[74:75] op_sel_hi:[1,0]
	v_cndmask_b32_e32 v9, v72, v9, vcc
	v_rsq_f32_e32 v9, v9
	v_mov_b32_e32 v0, v184
	v_mov_b32_e32 v1, v185
	v_mov_b32_e32 v2, v186
	v_mov_b32_e32 v3, v187
	v_mov_b32_e32 v4, v200
	v_mov_b32_e32 v5, v201
	v_mov_b32_e32 v6, v202
	v_mov_b32_e32 v7, v203
	v_pk_fma_f32 v[0:1], v[40:41], v[0:1], v[4:5]
	v_pk_fma_f32 v[2:3], v[42:43], v[2:3], v[6:7]
	global_store_dwordx4 v[32:33], v[0:3], off offset:2048
	v_pk_mul_f32 v[40:41], v[52:53], v[74:75] op_sel_hi:[1,0]
	v_pk_mul_f32 v[42:43], v[54:55], v[74:75] op_sel_hi:[1,0]
	v_mov_b32_e32 v0, v188
	v_mov_b32_e32 v1, v189
	v_mov_b32_e32 v2, v190
	v_mov_b32_e32 v3, v191
	v_mov_b32_e32 v4, v204
	v_mov_b32_e32 v5, v205
	v_mov_b32_e32 v6, v206
	v_mov_b32_e32 v7, v207
	v_pk_fma_f32 v[0:1], v[40:41], v[0:1], v[4:5]
	v_pk_fma_f32 v[2:3], v[42:43], v[2:3], v[6:7]
	global_store_dwordx4 v[32:33], v[0:3], off offset:3072
	v_mul_f32_e32 v32, 0x45800000, v9
	v_cndmask_b32_e32 v32, v9, v32, vcc
	v_pk_mul_f32 v[40:41], v[56:57], v[32:33] op_sel_hi:[1,0]
	v_pk_mul_f32 v[42:43], v[58:59], v[32:33] op_sel_hi:[1,0]
	v_cmp_lt_i32_e32 vcc, s8, v8
	s_or_b64 s[0:1], vcc, s[0:1]
	v_mov_b32_e32 v0, v176
	v_mov_b32_e32 v1, v177
	v_mov_b32_e32 v2, v178
	v_mov_b32_e32 v3, v179
	v_mov_b32_e32 v4, v192
	v_mov_b32_e32 v5, v193
	v_mov_b32_e32 v6, v194
	v_mov_b32_e32 v7, v195
	v_pk_fma_f32 v[0:1], v[0:1], v[40:41], v[4:5]
	v_pk_fma_f32 v[2:3], v[2:3], v[42:43], v[6:7]
	global_store_dwordx4 v[30:31], v[0:3], off
	v_pk_mul_f32 v[40:41], v[60:61], v[32:33] op_sel_hi:[1,0]
	v_pk_mul_f32 v[42:43], v[62:63], v[32:33] op_sel_hi:[1,0]
	v_mov_b32_e32 v0, v180
	v_mov_b32_e32 v1, v181
	v_mov_b32_e32 v2, v182
	v_mov_b32_e32 v3, v183
	v_mov_b32_e32 v4, v196
	v_mov_b32_e32 v5, v197
	v_mov_b32_e32 v6, v198
	v_mov_b32_e32 v7, v199
	v_pk_fma_f32 v[0:1], v[0:1], v[40:41], v[4:5]
	v_pk_fma_f32 v[2:3], v[2:3], v[42:43], v[6:7]
	global_store_dwordx4 v[30:31], v[0:3], off offset:1024
	v_pk_mul_f32 v[40:41], v[64:65], v[32:33] op_sel_hi:[1,0]
	v_pk_mul_f32 v[42:43], v[66:67], v[32:33] op_sel_hi:[1,0]
	v_mov_b32_e32 v0, v184
	v_mov_b32_e32 v1, v185
	v_mov_b32_e32 v2, v186
	v_mov_b32_e32 v3, v187
	v_mov_b32_e32 v4, v200
	v_mov_b32_e32 v5, v201
	v_mov_b32_e32 v6, v202
	v_mov_b32_e32 v7, v203
	v_pk_fma_f32 v[0:1], v[40:41], v[0:1], v[4:5]
	v_pk_fma_f32 v[2:3], v[42:43], v[2:3], v[6:7]
	global_store_dwordx4 v[30:31], v[0:3], off offset:2048
	v_pk_mul_f32 v[40:41], v[68:69], v[32:33] op_sel_hi:[1,0]
	v_pk_mul_f32 v[32:33], v[70:71], v[32:33] op_sel_hi:[1,0]
	v_mov_b32_e32 v0, v188
	v_mov_b32_e32 v1, v189
	v_mov_b32_e32 v2, v190
	v_mov_b32_e32 v3, v191
	v_mov_b32_e32 v4, v204
	v_mov_b32_e32 v5, v205
	v_mov_b32_e32 v6, v206
	v_mov_b32_e32 v7, v207
	v_pk_fma_f32 v[0:1], v[40:41], v[0:1], v[4:5]
	v_pk_fma_f32 v[2:3], v[32:33], v[2:3], v[6:7]
	global_store_dwordx4 v[30:31], v[0:3], off offset:3072
	s_andn2_b64 exec, exec, s[0:1]
	s_cbranch_execnz .LBB0_1319
